# v15 plus per-lane softmax row-sum accumulation (cross-half permlane swap once per item instead of per tile) and saddr-form K/V tile loads in the attention loops
# speedup vs baseline: 1.0240x; 1.0014x over previous
; #define SBAR() __builtin_amdgcn_sched_barrier(0)
; #define SWAIT() asm volatile("s_waitcnt vmcnt(3)" ::: "memory")
; #define VSEG(j) do { rowmax_adjust(S0, S1, m2, negm, alpha, (j) == 0); RESC(alpha); l_reg = l_reg * alpha + exp_pack(S0, S1, pa0, pa1, pa2, pa3); } while (0)
; template <bool MLA>
; __device__ __forceinline__ void attn_core(const bf16_t* __restrict__ Qb, const bf16_t* __restrict__ Kh, const bf16_t* __restrict__ Vh, int seq, char* lds,
;                                           f32x16 (&o)[Cfg<MLA>::NCB], const int wid  , const int g  ) {
;     ...
;         SBAR(); VSEG(j + 1);
;         SWAIT(); if (j + 3 < NT) SWRITE(((j + 3) % 3) * SHM_K, ((j + 3) & 3) * SHM_V, SO);
;         if (!(MLA && PROBE_NOLOAD)) { const int tn = (j + 5 < NT) ? j + 5 : NT - 1; SLOAD(SO, tn * 64); } SBAR();
;         __syncthreads();
;     }
.LBB0_1149:
	s_min_u32 s0, s95, 0x7e
	s_lshl_b32 s0, s0, 16
	s_add_i32 s16, s0, 0x50000
	s_add_u32 s0, s58, s16
	s_addc_u32 s1, s59, 0
	v_fma_f32 v82, v215, v184, v185
	v_fma_f32 v215, v82, v187, v80
	global_load_dwordx4 v[140:143], v200, s[0:1]
	global_load_dwordx4 v[144:147], v202, s[0:1]
	v_lshl_add_u64 v[80:81], v[204:205], 0, s[16:17]
	global_load_dwordx4 v[148:151], v[80:81], off
	s_add_i32 s94, s94, 2
	s_add_i32 s51, s51, 0x8000
	s_cmpk_gt_u32 s95, 0x81
	s_waitcnt lgkmcnt(0)
	s_barrier
	s_cbranch_scc1 .LBB0_1173

; #define SBAR() __builtin_amdgcn_sched_barrier(0)
; #define PK4(P, BASE, OUT) do { u32x4 w = {cvtpk_a(P[BASE + 0], P[BASE + 1]), cvtpk_a(P[BASE + 2], P[BASE + 3]), cvtpk_a(P[BASE + 4], P[BASE + 5]), cvtpk_a(P[BASE + 6], P[BASE + 7])}; \
;     OUT = *reinterpret_cast<bf16x8*>(&w); } while (0)
; #define SWAIT() asm volatile("s_waitcnt vmcnt(3)" ::: "memory")
; __device__ __forceinline__ float exp_pack(f32x16& p0, f32x16& p1, bf16x8& pa0, bf16x8& pa1, bf16x8& pa2, bf16x8& pa3) {
; #pragma unroll
;     for (int r = 0; r < 16; ++r) p0[r] = __builtin_amdgcn_exp2f(p0[r]);
; #pragma unroll
;     for (int r = 0; r < 16; ++r) p1[r] = __builtin_amdgcn_exp2f(p1[r]);
;     SBAR(); asm volatile("s_nop 1" ::: "memory"); SBAR();
;     ...
;     PK4(p0, 0, pa0); PK4(p0, 8, pa1); PK4(p1, 0, pa2); PK4(p1, 8, pa3);
;     ...
;     float ps0 = p0[0], ps1 = p1[0];
; #pragma unroll
;     for (int r = 1; r < 16; ++r) { ps0 += p0[r]; ps1 += p1[r]; }
;     float ps = ps0 + ps1;
;     { auto rr = __builtin_amdgcn_permlane32_swap(__float_as_uint(ps), __float_as_uint(ps), false, false);
;       ps = __uint_as_float(rr[0]) + __uint_as_float(rr[1]); }
;     return ps;
; template <bool MLA>
; __device__ __forceinline__ void attn_core(const bf16_t* __restrict__ Qb, const bf16_t* __restrict__ Kh, const bf16_t* __restrict__ Vh, int seq, char* lds,
;                                           f32x16 (&o)[Cfg<MLA>::NCB], const int wid  , const int g  ) {
;     ...
;         SWAIT(); if (j + 2 < NT) SWRITE(((j + 2) % 3) * SHM_K, ((j + 2) & 3) * SHM_V, SE);
.LBB0_1162:
	v_exp_f32_e32 v96, v96
	v_exp_f32_e32 v97, v97
	v_exp_f32_e32 v98, v98
	v_exp_f32_e32 v99, v99
	v_exp_f32_e32 v100, v100
	v_exp_f32_e32 v101, v101
	v_exp_f32_e32 v102, v102
	v_exp_f32_e32 v103, v103
	v_exp_f32_e32 v104, v104
	v_exp_f32_e32 v105, v105
	v_exp_f32_e32 v106, v106
	v_exp_f32_e32 v107, v107
	v_exp_f32_e32 v108, v108
	v_exp_f32_e32 v109, v109
	v_exp_f32_e32 v110, v110
	v_exp_f32_e32 v111, v111
	v_exp_f32_e32 v80, v80
	v_exp_f32_e32 v81, v81
	v_exp_f32_e32 v82, v82
	v_exp_f32_e32 v83, v83
	v_exp_f32_e32 v84, v84
	v_exp_f32_e32 v85, v85
	v_exp_f32_e32 v86, v86
	v_exp_f32_e32 v87, v87
	v_exp_f32_e32 v88, v88
	v_exp_f32_e32 v89, v89
	v_exp_f32_e32 v90, v90
	v_exp_f32_e32 v91, v91
	v_exp_f32_e32 v92, v92
	v_exp_f32_e32 v93, v93
	v_exp_f32_e32 v94, v94
	v_exp_f32_e32 v95, v95
	s_nop 1
	v_cvt_pk_bf16_f32 v180, v96, v97
	v_cvt_pk_bf16_f32 v181, v98, v99
	v_cvt_pk_bf16_f32 v182, v100, v101
	v_cvt_pk_bf16_f32 v183, v102, v103
	v_cvt_pk_bf16_f32 v176, v104, v105
	v_cvt_pk_bf16_f32 v177, v106, v107
	v_cvt_pk_bf16_f32 v178, v108, v109
	v_cvt_pk_bf16_f32 v179, v110, v111
	v_cvt_pk_bf16_f32 v172, v80, v81
	v_add_f32_e32 v96, v96, v97
	v_add_f32_e32 v80, v80, v81
	v_add_f32_e32 v81, v98, v96
	v_add_f32_e32 v80, v82, v80
	v_add_f32_e32 v81, v99, v81
	v_add_f32_e32 v80, v83, v80
	v_add_f32_e32 v81, v100, v81
	v_add_f32_e32 v80, v84, v80
	v_add_f32_e32 v81, v101, v81
	v_add_f32_e32 v80, v85, v80
	v_add_f32_e32 v81, v102, v81
	v_add_f32_e32 v80, v86, v80
	v_add_f32_e32 v81, v103, v81
	v_add_f32_e32 v80, v87, v80
	v_add_f32_e32 v81, v104, v81
	v_add_f32_e32 v80, v88, v80
	v_add_f32_e32 v81, v105, v81
	v_add_f32_e32 v80, v89, v80
	v_add_f32_e32 v81, v106, v81
	v_add_f32_e32 v80, v90, v80
	v_add_f32_e32 v81, v107, v81
	v_add_f32_e32 v80, v91, v80
	v_add_f32_e32 v81, v108, v81
	v_add_f32_e32 v80, v92, v80
	v_add_f32_e32 v81, v109, v81
	v_add_f32_e32 v80, v93, v80
	v_add_f32_e32 v81, v110, v81
	v_add_f32_e32 v80, v94, v80
	v_add_f32_e32 v81, v111, v81
	v_add_f32_e32 v80, v95, v80
	v_cvt_pk_bf16_f32 v173, v82, v83
	v_cvt_pk_bf16_f32 v174, v84, v85
	v_cvt_pk_bf16_f32 v175, v86, v87
	v_cvt_pk_bf16_f32 v168, v88, v89
	v_cvt_pk_bf16_f32 v169, v90, v91
	v_cvt_pk_bf16_f32 v170, v92, v93
	v_cvt_pk_bf16_f32 v171, v94, v95
	v_add_f32_e32 v185, v80, v81
	s_waitcnt vmcnt(3)
	s_cmpk_gt_u32 s95, 0x81
	s_cbranch_scc1 .LBB0_1164
	s_add_i32 s0, s51, 0x8000
	s_and_b32 s0, s0, 0x8000
	s_add_i32 s0, s0, 0
	v_add_u32_e32 v80, s0, v210
	s_waitcnt vmcnt(5)
	ds_write_b128 v80, v[132:135]
	v_add_u32_e32 v80, s0, v211
	s_add_i32 s0, s94, 0xffff
	s_mul_i32 s1, s0, 0xab
	s_bfe_u32 s1, s1, 0x70009
	s_mul_i32 s1, s1, 3
	s_sub_i32 s0, s0, s1
	s_and_b32 s0, s0, 0xff
	s_mulk_i32 s0, 0x2400
	s_waitcnt vmcnt(4)
	ds_write_b128 v80, v[128:131]
	v_add_u32_e32 v80, s0, v212
	s_waitcnt vmcnt(3)
	ds_write_b128 v80, v[136:139]
; __device__ __forceinline__ float max3f(float a, float b, float c) { return __builtin_fmaxf(__builtin_fmaxf(a, b), c); }
; __device__ __forceinline__ void rowmax_adjust(f32x16& p0, f32x16& p1, float& m2, f32x16& negm, float& alpha, const bool first) {
;     ...
;     float pmax = max3f(p0[0], p0[1], p0[2]);
; #pragma unroll
;     for (int r = 3; r < 15; r += 2) pmax = max3f(pmax, p0[r], p0[r + 1]);
;     pmax = max3f(pmax, p0[15], p1[0]);
; #pragma unroll
;     for (int r = 1; r < 15; r += 2) pmax = max3f(pmax, p1[r], p1[r + 1]);
;     pmax = fmaxf(pmax, p1[15]);
;     { auto rr = __builtin_amdgcn_permlane32_swap(__float_as_uint(pmax), __float_as_uint(pmax), false, false);
;       pmax = fmaxf(__uint_as_float(rr[0]), __uint_as_float(rr[1])); }
;     if (!first && __builtin_expect(__all(pmax <= THR2), 1)) { alpha = 1.f; }
.LBB0_1164:
	s_min_u32 s0, s95, 0x7f
	s_lshl_b32 s0, s0, 16
	s_add_i32 s16, s0, 0x40000
	s_add_u32 s0, s58, s16
	s_addc_u32 s1, s59, 0
	global_load_dwordx4 v[132:135], v200, s[0:1]
	global_load_dwordx4 v[128:131], v202, s[0:1]
	v_lshl_add_u64 v[80:81], v[204:205], 0, s[16:17]
	global_load_dwordx4 v[136:139], v[80:81], off
	s_waitcnt lgkmcnt(0)
	s_barrier
	s_or_b32 s0, s95, 1
	s_and_b32 s1, s0, 0xff
	s_mulk_i32 s1, 0xab
	s_bfe_u32 s1, s1, 0x70009
	s_mul_i32 s1, s1, 3
	s_sub_i32 s0, s0, s1
	s_and_b32 s0, s0, 0xff
	s_mulk_i32 s0, 0x2400
	v_add_u32_e32 v84, s0, v218
	s_and_b32 s0, s51, 0x8000
	v_add_u32_e32 v187, s0, v217
	ds_read_b128 v[80:83], v84
	ds_read_b128 v[192:195], v84 offset:4608
	ds_read_b128 v[188:191], v84 offset:32
	ds_read_b128 v[196:199], v84 offset:4640
	ds_read_b128 v[220:223], v84 offset:64
	ds_read_b128 v[228:231], v84 offset:4672
	ds_read_b128 v[224:227], v84 offset:96
	ds_read_b128 v[232:235], v84 offset:4704
	ds_read_b64_tr_b16 v[164:165], v187 offset:0
	ds_read_b64_tr_b16 v[166:167], v187 offset:0x800
	ds_read_b64_tr_b16 v[160:161], v187 offset:0x1000
	ds_read_b64_tr_b16 v[162:163], v187 offset:0x1800
	ds_read_b64_tr_b16 v[156:157], v187 offset:0x2000
	ds_read_b64_tr_b16 v[158:159], v187 offset:0x2800
	ds_read_b64_tr_b16 v[152:153], v187 offset:0x3000
	ds_read_b64_tr_b16 v[154:155], v187 offset:0x3800
	s_waitcnt lgkmcnt(15)
	v_mfma_f32_32x32x16_bf16 v[96:111], v[80:83], v[112:115], v[64:79]
	s_waitcnt lgkmcnt(14)
	v_mfma_f32_32x32x16_bf16 v[80:95], v[192:195], v[112:115], v[64:79]
	s_waitcnt lgkmcnt(13)
	v_mfma_f32_32x32x16_bf16 v[96:111], v[188:191], v[116:119], v[96:111]
	s_waitcnt lgkmcnt(12)
	v_mfma_f32_32x32x16_bf16 v[80:95], v[196:199], v[116:119], v[80:95]
	s_waitcnt lgkmcnt(8)
	ds_read_b64_tr_b16 v[188:189], v187 offset:0x200
	ds_read_b64_tr_b16 v[190:191], v187 offset:0xa00
	ds_read_b64_tr_b16 v[192:193], v187 offset:0x1200
	ds_read_b64_tr_b16 v[194:195], v187 offset:0x1a00
	ds_read_b64_tr_b16 v[196:197], v187 offset:0x2200
	ds_read_b64_tr_b16 v[198:199], v187 offset:0x2a00
	ds_read_b64_tr_b16 v[236:237], v187 offset:0x3200
	ds_read_b64_tr_b16 v[238:239], v187 offset:0x3a00
	v_mfma_f32_32x32x16_bf16 v[96:111], v[220:223], v[120:123], v[96:111]
	v_mfma_f32_32x32x16_bf16 v[80:95], v[228:231], v[120:123], v[80:95]
	v_mfma_f32_32x32x16_bf16 v[96:111], v[224:227], v[124:127], v[96:111]
	v_mfma_f32_32x32x16_bf16 v[80:95], v[232:235], v[124:127], v[80:95]
	ds_read_b64_tr_b16 v[220:221], v187 offset:0x600
	ds_read_b64_tr_b16 v[222:223], v187 offset:0xe00
	ds_read_b64_tr_b16 v[224:225], v187 offset:0x1600
	ds_read_b64_tr_b16 v[226:227], v187 offset:0x1e00
	ds_read_b64_tr_b16 v[228:229], v187 offset:0x2600
	ds_read_b64_tr_b16 v[230:231], v187 offset:0x2e00
	ds_read_b64_tr_b16 v[232:233], v187 offset:0x3600
	ds_read_b64_tr_b16 v[234:235], v187 offset:0x3e00
	s_waitcnt lgkmcnt(15)
	v_mfma_f32_32x32x16_bf16 v[48:63], v[180:183], v[164:167], v[48:63]
	v_mfma_f32_32x32x16_bf16 v[48:63], v[176:179], v[160:163], v[48:63]
	v_mfma_f32_32x32x16_bf16 v[48:63], v[172:175], v[156:159], v[48:63]
	v_mfma_f32_32x32x16_bf16 v[48:63], v[168:171], v[152:155], v[48:63]
	ds_read_b64_tr_b16 v[164:165], v187 offset:0x400
	ds_read_b64_tr_b16 v[166:167], v187 offset:0xc00
	ds_read_b64_tr_b16 v[160:161], v187 offset:0x1400
	ds_read_b64_tr_b16 v[162:163], v187 offset:0x1c00
	ds_read_b64_tr_b16 v[156:157], v187 offset:0x2400
	ds_read_b64_tr_b16 v[158:159], v187 offset:0x2c00
	ds_read_b64_tr_b16 v[152:153], v187 offset:0x3400
	ds_read_b64_tr_b16 v[154:155], v187 offset:0x3c00
	s_waitcnt lgkmcnt(15)
	v_mfma_f32_32x32x16_bf16 v[32:47], v[180:183], v[188:191], v[32:47]
	v_mfma_f32_32x32x16_bf16 v[32:47], v[176:179], v[192:195], v[32:47]
	v_mfma_f32_32x32x16_bf16 v[32:47], v[172:175], v[196:199], v[32:47]
	v_mfma_f32_32x32x16_bf16 v[32:47], v[168:171], v[236:239], v[32:47]
	s_waitcnt lgkmcnt(8)
	v_mfma_f32_32x32x16_bf16 v[0:15], v[180:183], v[220:223], v[0:15]
	v_mfma_f32_32x32x16_bf16 v[0:15], v[176:179], v[224:227], v[0:15]
	v_mfma_f32_32x32x16_bf16 v[0:15], v[172:175], v[228:231], v[0:15]
	v_mfma_f32_32x32x16_bf16 v[0:15], v[168:171], v[232:235], v[0:15]
	s_waitcnt lgkmcnt(0)
	v_mfma_f32_32x32x16_bf16 v[16:31], v[180:183], v[164:167], v[16:31]
	v_mfma_f32_32x32x16_bf16 v[16:31], v[176:179], v[160:163], v[16:31]
	v_mfma_f32_32x32x16_bf16 v[16:31], v[172:175], v[156:159], v[16:31]
	v_mfma_f32_32x32x16_bf16 v[16:31], v[168:171], v[152:155], v[16:31]
	s_barrier
	v_max3_f32 v168, v96, v97, v98
	v_max3_f32 v169, v81, v82, v83
	v_max3_f32 v168, v168, v99, v100
	v_max3_f32 v169, v169, v84, v85
	v_max3_f32 v168, v168, v101, v102
	v_max3_f32 v169, v169, v86, v87
	v_max3_f32 v168, v168, v103, v104
	v_max3_f32 v169, v169, v88, v89
	v_max3_f32 v168, v168, v105, v106
	v_max3_f32 v169, v169, v90, v91
	v_max3_f32 v168, v168, v107, v108
	v_max3_f32 v169, v169, v92, v93
	v_max3_f32 v168, v168, v109, v110
	v_max3_f32 v169, v169, v94, v95
	v_max3_f32 v168, v168, v111, v80
	v_max_f32_e32 v168, v168, v169
	v_mov_b32_e32 v169, v168
	s_nop 1
	v_permlane32_swap_b32_e32 v168, v169
	v_max_f32_e32 v168, v168, v169
	v_cmp_ge_f32_e32 vcc, s83, v168
	v_mov_b32_e32 v187, 1.0
	s_cmp_eq_u64 vcc, exec
	s_cbranch_scc1 .LBB0_1169
	s_branch .LBB0_1171

; #define SBAR() __builtin_amdgcn_sched_barrier(0)
; #define PK4(P, BASE, OUT) do { u32x4 w = {cvtpk_a(P[BASE + 0], P[BASE + 1]), cvtpk_a(P[BASE + 2], P[BASE + 3]), cvtpk_a(P[BASE + 4], P[BASE + 5]), cvtpk_a(P[BASE + 6], P[BASE + 7])}; \
;     OUT = *reinterpret_cast<bf16x8*>(&w); } while (0)
; #define SWAIT() asm volatile("s_waitcnt vmcnt(3)" ::: "memory")
; __device__ __forceinline__ float exp_pack(f32x16& p0, f32x16& p1, bf16x8& pa0, bf16x8& pa1, bf16x8& pa2, bf16x8& pa3) {
; #pragma unroll
;     for (int r = 0; r < 16; ++r) p0[r] = __builtin_amdgcn_exp2f(p0[r]);
; #pragma unroll
;     for (int r = 0; r < 16; ++r) p1[r] = __builtin_amdgcn_exp2f(p1[r]);
;     SBAR(); asm volatile("s_nop 1" ::: "memory"); SBAR();
;     ...
;     PK4(p0, 0, pa0); PK4(p0, 8, pa1); PK4(p1, 0, pa2); PK4(p1, 8, pa3);
;     ...
;     float ps0 = p0[0], ps1 = p1[0];
; #pragma unroll
;     for (int r = 1; r < 16; ++r) { ps0 += p0[r]; ps1 += p1[r]; }
;     float ps = ps0 + ps1;
;     { auto rr = __builtin_amdgcn_permlane32_swap(__float_as_uint(ps), __float_as_uint(ps), false, false);
;       ps = __uint_as_float(rr[0]) + __uint_as_float(rr[1]); }
;     return ps;
; template <bool MLA>
; __device__ __forceinline__ void attn_core(const bf16_t* __restrict__ Qb, const bf16_t* __restrict__ Kh, const bf16_t* __restrict__ Vh, int seq, char* lds,
;                                           f32x16 (&o)[Cfg<MLA>::NCB], const int wid  , const int g  ) {
;     ...
;         SWAIT(); if (j + 3 < NT) SWRITE(((j + 3) % 3) * SHM_K, ((j + 3) & 3) * SHM_V, SO);
.LBB0_1169:
	v_exp_f32_e32 v80, v80
	v_exp_f32_e32 v81, v81
	v_exp_f32_e32 v96, v96
	v_exp_f32_e32 v97, v97
	v_exp_f32_e32 v98, v98
	v_exp_f32_e32 v99, v99
	v_exp_f32_e32 v100, v100
	v_exp_f32_e32 v101, v101
	v_exp_f32_e32 v102, v102
	v_exp_f32_e32 v103, v103
	v_exp_f32_e32 v104, v104
	v_exp_f32_e32 v105, v105
	v_exp_f32_e32 v106, v106
	v_exp_f32_e32 v107, v107
	v_exp_f32_e32 v108, v108
	v_exp_f32_e32 v109, v109
	v_exp_f32_e32 v110, v110
	v_exp_f32_e32 v111, v111
	v_exp_f32_e32 v82, v82
	v_exp_f32_e32 v83, v83
	v_exp_f32_e32 v84, v84
	v_exp_f32_e32 v85, v85
	v_exp_f32_e32 v86, v86
	v_exp_f32_e32 v87, v87
	v_exp_f32_e32 v88, v88
	v_exp_f32_e32 v89, v89
	v_exp_f32_e32 v90, v90
	v_exp_f32_e32 v91, v91
	v_exp_f32_e32 v92, v92
	v_exp_f32_e32 v93, v93
	v_exp_f32_e32 v94, v94
	v_exp_f32_e32 v95, v95
	s_nop 1
	v_cvt_pk_bf16_f32 v180, v96, v97
	v_cvt_pk_bf16_f32 v181, v98, v99
	v_cvt_pk_bf16_f32 v182, v100, v101
	v_cvt_pk_bf16_f32 v183, v102, v103
	v_cvt_pk_bf16_f32 v176, v104, v105
	v_cvt_pk_bf16_f32 v177, v106, v107
	v_cvt_pk_bf16_f32 v178, v108, v109
	v_cvt_pk_bf16_f32 v179, v110, v111
	v_cvt_pk_bf16_f32 v172, v80, v81
	v_add_f32_e32 v96, v96, v97
	v_add_f32_e32 v80, v80, v81
	v_add_f32_e32 v81, v98, v96
	v_add_f32_e32 v80, v82, v80
	v_add_f32_e32 v81, v99, v81
	v_add_f32_e32 v80, v83, v80
	v_add_f32_e32 v81, v100, v81
	v_add_f32_e32 v80, v84, v80
	v_add_f32_e32 v81, v101, v81
	v_add_f32_e32 v80, v85, v80
	v_add_f32_e32 v81, v102, v81
	v_add_f32_e32 v80, v86, v80
	v_add_f32_e32 v81, v103, v81
	v_add_f32_e32 v80, v87, v80
	v_add_f32_e32 v81, v104, v81
	v_add_f32_e32 v80, v88, v80
	v_add_f32_e32 v81, v105, v81
	v_add_f32_e32 v80, v89, v80
	v_add_f32_e32 v81, v106, v81
	v_add_f32_e32 v80, v90, v80
	v_add_f32_e32 v81, v107, v81
	v_add_f32_e32 v80, v91, v80
	v_add_f32_e32 v81, v108, v81
	v_add_f32_e32 v80, v92, v80
	v_add_f32_e32 v81, v109, v81
	v_add_f32_e32 v80, v93, v80
	v_add_f32_e32 v81, v110, v81
	v_add_f32_e32 v80, v94, v80
	v_add_f32_e32 v81, v111, v81
	v_add_f32_e32 v80, v95, v80
	v_cvt_pk_bf16_f32 v173, v82, v83
	v_cvt_pk_bf16_f32 v174, v84, v85
	v_cvt_pk_bf16_f32 v175, v86, v87
	v_cvt_pk_bf16_f32 v168, v88, v89
	v_cvt_pk_bf16_f32 v169, v90, v91
	v_cvt_pk_bf16_f32 v170, v92, v93
	v_cvt_pk_bf16_f32 v171, v94, v95
	v_add_f32_e32 v80, v80, v81
	s_waitcnt vmcnt(3)
	s_cmpk_gt_u32 s95, 0x80
	s_cbranch_scc1 .LBB0_1149
	s_add_i32 s0, s96, 0
	v_add_u32_e32 v82, s0, v210
	s_waitcnt vmcnt(5)
	ds_write_b128 v82, v[140:143]
	v_add_u32_e32 v82, s0, v211
	s_mul_i32 s0, s94, 0xab
	s_bfe_u32 s0, s0, 0x70009
	s_mul_i32 s0, s0, 3
	s_sub_i32 s0, s94, s0
	s_and_b32 s0, s0, 0xff
	s_mulk_i32 s0, 0x2400
	s_waitcnt vmcnt(4)
	ds_write_b128 v82, v[144:147]
	v_add_u32_e32 v82, s0, v212
	s_waitcnt vmcnt(3)
	ds_write_b128 v82, v[148:151]
	s_branch .LBB0_1149

; __device__ __forceinline__ int lane_id_v() { int l; asm volatile("v_mbcnt_lo_u32_b32 %0, -1, 0\n\tv_mbcnt_hi_u32_b32 %0, -1, %0" : "=v"(l)); return l; }
; __device__ __forceinline__ unsigned cvtpk(float lo, float hi) { f32x2_t v = {lo, hi}; bf16x2_t b = __builtin_convertvector(v, bf16x2_t); return __builtin_bit_cast(unsigned, b); }
; __device__ __forceinline__ int crow(int r, int hi) { return (r & 3) + 8 * (r >> 2) + 4 * hi; }
; template <bool MLA>
; __device__ __forceinline__ void attn_core(const bf16_t* __restrict__ Qb, const bf16_t* __restrict__ Kh, const bf16_t* __restrict__ Vh, int seq, char* lds,
;                                           f32x16 (&o)[Cfg<MLA>::NCB], const int wid  , const int g  ) {
;     ...
;     asm volatile("s_waitcnt vmcnt(0)" ::: "memory");
;     if (hi == 0) li_l[r32] = l_reg; asm volatile("s_waitcnt lgkmcnt(0)" ::: "memory");
; #pragma unroll
;     for (int r = 0; r < 16; ++r) { const float rl = __builtin_amdgcn_rcpf(li_l[crow(r, hi)]);
; #pragma unroll
;         for (int d = 0; d < NCB; ++d) o[d][r] *= rl; }
; __global__ void __launch_bounds__(512, 2) fwd_mega(Args a) {
;     ...
;                 { unsigned* stash = (unsigned*)(lds + 95232 + wave * 8192) + lane_id_v();
; #pragma unroll
;                 for (int d0 = 0; d0 < 4; ++d0)
; #pragma unroll
;                     for (int r = 0; r < 16; r += 2) stash[(d0 * 8 + (r >> 1)) * 64] = cvtpk(o[d0][r], o[d0][r + 1]); }
;                 att::attn_core<false>(DQ + qrow0 * 512 + h * 128 + 64, DK + krow0 * 512 + h * 128 + 64, DV + krow0 * 512 + h * 128, SKV, (char*)lds, o, wave, grp);
.LBB0_1175:
	s_waitcnt vmcnt(0)
	v_mov_b32_e32 v80, v215
	s_nop 1
	v_permlane32_swap_b32_e32 v215, v80
	v_add_f32_e32 v215, v215, v80
	s_and_saveexec_b64 s[0:1], s[4:5]
	v_readlane_b32 s96, v254, 49
	v_readlane_b32 s97, v254, 50
	ds_write_b32 v214, v215
	s_or_b64 exec, exec, s[0:1]
	s_waitcnt lgkmcnt(0)
	v_add_u32_e32 v72, s42, v213
	ds_read_b128 v[64:67], v72
	ds_read_b128 v[68:71], v72 offset:32
	s_mov_b32 s0, s18
	s_waitcnt lgkmcnt(1)
	v_rcp_f32_e32 v64, v64
	v_rcp_f32_e32 v65, v65
	s_nop 0
	v_pk_mul_f32 v[48:49], v[64:65], v[48:49]
	v_pk_mul_f32 v[32:33], v[64:65], v[32:33]
	v_pk_mul_f32 v[16:17], v[64:65], v[16:17]
	v_pk_mul_f32 v[0:1], v[64:65], v[0:1]
	v_rcp_f32_e32 v64, v66
	v_rcp_f32_e32 v65, v67
	v_cvt_pk_bf16_f32 v0, v0, v1
	v_pk_mul_f32 v[50:51], v[64:65], v[50:51]
	v_pk_mul_f32 v[34:35], v[64:65], v[34:35]
	v_pk_mul_f32 v[18:19], v[64:65], v[18:19]
	v_pk_mul_f32 v[2:3], v[64:65], v[2:3]
	s_waitcnt lgkmcnt(0)
	v_rcp_f32_e32 v64, v68
	v_rcp_f32_e32 v65, v69
	v_cvt_pk_bf16_f32 v1, v2, v3
	v_pk_mul_f32 v[52:53], v[64:65], v[52:53]
	v_pk_mul_f32 v[36:37], v[64:65], v[36:37]
	v_pk_mul_f32 v[20:21], v[64:65], v[20:21]
	v_pk_mul_f32 v[4:5], v[64:65], v[4:5]
	v_rcp_f32_e32 v64, v70
	v_rcp_f32_e32 v65, v71
	s_nop 0
	v_pk_mul_f32 v[54:55], v[64:65], v[54:55]
	v_pk_mul_f32 v[38:39], v[64:65], v[38:39]
	v_pk_mul_f32 v[22:23], v[64:65], v[22:23]
	v_pk_mul_f32 v[6:7], v[64:65], v[6:7]
	ds_read_b128 v[64:67], v72 offset:64
	s_waitcnt lgkmcnt(0)
	v_rcp_f32_e32 v64, v64
	v_rcp_f32_e32 v65, v65
	s_nop 0
	v_pk_mul_f32 v[56:57], v[64:65], v[56:57]
	v_pk_mul_f32 v[40:41], v[64:65], v[40:41]
	v_pk_mul_f32 v[24:25], v[64:65], v[24:25]
	v_pk_mul_f32 v[64:65], v[64:65], v[8:9]
	v_rcp_f32_e32 v8, v66
	v_rcp_f32_e32 v9, v67
	s_nop 0
	v_pk_mul_f32 v[58:59], v[8:9], v[58:59]
	v_pk_mul_f32 v[42:43], v[8:9], v[42:43]
	v_pk_mul_f32 v[26:27], v[8:9], v[26:27]
	v_pk_mul_f32 v[66:67], v[8:9], v[10:11]
	ds_read_b128 v[8:11], v72 offset:96
	s_waitcnt lgkmcnt(0)
	v_rcp_f32_e32 v8, v8
	v_rcp_f32_e32 v9, v9
	v_rcp_f32_e32 v10, v10
	v_rcp_f32_e32 v11, v11
	v_pk_mul_f32 v[60:61], v[8:9], v[60:61]
	v_pk_mul_f32 v[44:45], v[8:9], v[44:45]
	v_pk_mul_f32 v[28:29], v[8:9], v[28:29]
	v_pk_mul_f32 v[8:9], v[8:9], v[12:13]
	v_pk_mul_f32 v[12:13], v[10:11], v[62:63]
	v_pk_mul_f32 v[46:47], v[10:11], v[46:47]
	v_pk_mul_f32 v[30:31], v[10:11], v[30:31]
	v_pk_mul_f32 v[10:11], v[10:11], v[14:15]
	v_mbcnt_lo_u32_b32 v14, -1, 0
	v_mbcnt_hi_u32_b32 v14, -1, v14
	v_cvt_pk_bf16_f32 v15, v48, v49
	v_lshl_add_u32 v14, v14, 2, s43
	v_cvt_pk_bf16_f32 v48, v50, v51
	ds_write2st64_b32 v14, v15, v48 offset1:1
	v_cvt_pk_bf16_f32 v15, v52, v53
	v_cvt_pk_bf16_f32 v48, v54, v55
	ds_write2st64_b32 v14, v15, v48 offset0:2 offset1:3
	v_cvt_pk_bf16_f32 v15, v56, v57
	v_cvt_pk_bf16_f32 v48, v58, v59
	ds_write2st64_b32 v14, v15, v48 offset0:4 offset1:5
	v_cvt_pk_bf16_f32 v15, v60, v61
	v_cvt_pk_bf16_f32 v12, v12, v13
	ds_write2st64_b32 v14, v15, v12 offset0:6 offset1:7
	v_cvt_pk_bf16_f32 v12, v32, v33
	v_cvt_pk_bf16_f32 v13, v34, v35
	ds_write2st64_b32 v14, v12, v13 offset0:8 offset1:9
	v_cvt_pk_bf16_f32 v12, v36, v37
	v_cvt_pk_bf16_f32 v13, v38, v39
	ds_write2st64_b32 v14, v12, v13 offset0:10 offset1:11
	v_cvt_pk_bf16_f32 v12, v40, v41
	v_cvt_pk_bf16_f32 v13, v42, v43
	ds_write2st64_b32 v14, v12, v13 offset0:12 offset1:13
	v_cvt_pk_bf16_f32 v12, v44, v45
	v_cvt_pk_bf16_f32 v13, v46, v47
	ds_write2st64_b32 v14, v12, v13 offset0:14 offset1:15
	v_cvt_pk_bf16_f32 v12, v16, v17
	v_cvt_pk_bf16_f32 v13, v18, v19
	ds_write2st64_b32 v14, v12, v13 offset0:16 offset1:17
	v_cvt_pk_bf16_f32 v12, v20, v21
	v_cvt_pk_bf16_f32 v13, v22, v23
	ds_write2st64_b32 v14, v0, v1 offset0:24 offset1:25
	v_cvt_pk_bf16_f32 v0, v4, v5
	v_cvt_pk_bf16_f32 v1, v6, v7
	ds_write2st64_b32 v14, v12, v13 offset0:18 offset1:19
	v_cvt_pk_bf16_f32 v12, v24, v25
	v_cvt_pk_bf16_f32 v13, v26, v27
	ds_write2st64_b32 v14, v0, v1 offset0:26 offset1:27
	v_cvt_pk_bf16_f32 v0, v64, v65
	v_cvt_pk_bf16_f32 v1, v66, v67
	ds_write2st64_b32 v14, v12, v13 offset0:20 offset1:21
	v_cvt_pk_bf16_f32 v12, v28, v29
	v_cvt_pk_bf16_f32 v13, v30, v31
	ds_write2st64_b32 v14, v0, v1 offset0:28 offset1:29
	v_cvt_pk_bf16_f32 v0, v8, v9
	v_cvt_pk_bf16_f32 v1, v10, v11
	ds_write2st64_b32 v14, v12, v13 offset0:22 offset1:23
	ds_write2st64_b32 v14, v0, v1 offset0:30 offset1:31
	v_mbcnt_lo_u32_b32 v3, -1, 0
	v_mbcnt_hi_u32_b32 v3, -1, v3
	v_mov_b32_e32 v17, v201
	v_and_b32_e32 v2, 31, v3
	v_ashrrev_i32_e32 v4, 5, v3
	v_or_b32_e32 v200, s86, v2
	v_lshlrev_b64 v[0:1], 10, v[200:201]
	v_lshlrev_b32_e32 v6, 3, v4
	v_lshl_add_u64 v[0:1], s[62:63], 0, v[0:1]
	v_ashrrev_i32_e32 v7, 31, v6
	v_lshl_add_u64 v[0:1], v[6:7], 1, v[0:1]
	global_load_dwordx4 v[112:115], v[0:1], off offset:128
	global_load_dwordx4 v[116:119], v[0:1], off offset:160
	global_load_dwordx4 v[120:123], v[0:1], off offset:192
	global_load_dwordx4 v[124:127], v[0:1], off offset:224
	v_add_u32_e32 v0, s81, v3
	v_lshlrev_b32_e32 v5, 3, v3
	v_ashrrev_i32_e32 v1, 4, v0
	v_lshrrev_b32_e32 v6, 5, v0
	v_bfe_u32 v7, v5, 5, 2
	v_and_or_b32 v9, v6, s46, v7
	v_lshlrev_b32_e32 v10, 5, v1
	v_and_b32_e32 v6, 24, v5
	v_and_or_b32 v10, v10, s47, v6
	v_lshlrev_b32_e32 v10, 1, v10
	v_lshl_or_b32 v210, v9, 9, v10
	v_add_u32_e32 v9, 32, v1
	v_lshrrev_b32_e32 v11, 1, v9
	v_and_or_b32 v7, v11, s46, v7
	v_lshl_or_b32 v211, v7, 9, v10
	v_lshlrev_b32_e32 v7, 4, v3
	v_and_b32_e32 v8, 0x78, v5
	v_ashrrev_i32_e32 v0, 3, v0
	v_and_b32_e32 v32, 0x70, v7
	v_lshlrev_b32_e32 v8, 1, v8
	v_lshl_or_b32 v16, v0, 10, v32
	v_mul_lo_u32 v33, v0, s76
	v_lshl_or_b32 v200, v1, 10, v8
	v_lshl_add_u64 v[0:1], s[60:61], 0, v[16:17]
	v_lshl_or_b32 v202, v9, 10, v8
	s_waitcnt lgkmcnt(0)
	s_barrier
; template <bool MLA>
; __device__ __forceinline__ void attn_core(const bf16_t* __restrict__ Qb, const bf16_t* __restrict__ Kh, const bf16_t* __restrict__ Vh, int seq, char* lds,
;                                           f32x16 (&o)[Cfg<MLA>::NCB], const int wid  , const int g  ) {
;     ...
;     __syncthreads();
;     SLOAD(SE, 0); SLOAD(SO, 64); asm volatile("s_waitcnt vmcnt(0)" ::: "memory");
;     SWRITE(0, 0, SE); SWRITE(SHM_K, SHM_V, SO);
;     SLOAD(SE, 2 * 64); SLOAD(SO, 3 * 64);
;     __syncthreads();
;     { int g_ = g; asm volatile("" : "+s"(g_)); if (g_ == 1) __syncthreads(); }
	global_load_dwordx4 v[8:11], v200, s[58:59]
	global_load_dwordx4 v[12:15], v202, s[58:59]
	v_add_co_u32_e32 v28, vcc, s77, v0
	global_load_dwordx4 v[16:19], v16, s[60:61] offset:128
	s_nop 0
	global_load_dwordx4 v[20:23], v200, s[64:65]
	global_load_dwordx4 v[24:27], v202, s[64:65]
	v_addc_co_u32_e32 v29, vcc, 0, v1, vcc
	global_load_dwordx4 v[28:31], v[28:29], off offset:128
	v_add_u32_e32 v34, 0, v210
	s_waitcnt vmcnt(0)
	s_waitcnt vmcnt(5)
	ds_write_b128 v34, v[8:11]
	v_add3_u32 v9, v33, v32, 0
	v_add_u32_e32 v8, 0, v211
	v_add_u32_e32 v212, 0x10000, v9
	s_waitcnt vmcnt(4)
	ds_write_b128 v8, v[12:15]
	s_waitcnt vmcnt(3)
	ds_write_b128 v212, v[16:19]
	s_waitcnt vmcnt(2)
	ds_write_b128 v34, v[20:23] offset:16384
	s_waitcnt vmcnt(1)
	ds_write_b128 v8, v[24:27] offset:16384
	v_add_u32_e32 v8, 0x12400, v9
	s_waitcnt vmcnt(0)
	ds_write_b128 v8, v[28:31]
	v_add_co_u32_e32 v8, vcc, s78, v0
	global_load_dwordx4 v[132:135], v200, s[70:71]
	global_load_dwordx4 v[128:131], v202, s[70:71]
	v_addc_co_u32_e32 v9, vcc, 0, v1, vcc
	global_load_dwordx4 v[136:139], v[8:9], off offset:128
	global_load_dwordx4 v[140:143], v200, s[68:69]
	global_load_dwordx4 v[144:147], v202, s[68:69]
	v_add_co_u32_e32 v8, vcc, 0x30000, v0
	s_nop 1
	v_addc_co_u32_e32 v9, vcc, 0, v1, vcc
	global_load_dwordx4 v[148:151], v[8:9], off offset:128
	s_waitcnt lgkmcnt(0)
	s_barrier
	s_cmp_lg_u32 s0, 1
	s_cbranch_scc1 .LBB0_1179
	s_barrier

; #define SBAR() __builtin_amdgcn_sched_barrier(0)
; #define SWAIT() asm volatile("s_waitcnt vmcnt(3)" ::: "memory")
; #define VSEG(j) do { rowmax_adjust(S0, S1, m2, negm, alpha, (j) == 0); RESC(alpha); l_reg = l_reg * alpha + exp_pack(S0, S1, pa0, pa1, pa2, pa3); } while (0)
; template <bool MLA>
; __device__ __forceinline__ void attn_core(const bf16_t* __restrict__ Qb, const bf16_t* __restrict__ Kh, const bf16_t* __restrict__ Vh, int seq, char* lds,
;                                           f32x16 (&o)[Cfg<MLA>::NCB], const int wid  , const int g  ) {
;     ...
;         SBAR(); VSEG(j + 1);
;         SWAIT(); if (j + 3 < NT) SWRITE(((j + 3) % 3) * SHM_K, ((j + 3) & 3) * SHM_V, SO);
;         if (!(MLA && PROBE_NOLOAD)) { const int tn = (j + 5 < NT) ? j + 5 : NT - 1; SLOAD(SO, tn * 64); } SBAR();
;         __syncthreads();
;     }
.LBB0_1180:
	s_min_u32 s0, s64, 0x7e
	s_lshl_b32 s0, s0, 16
	s_add_i32 s16, s0, 0x50000
	s_add_u32 s0, s58, s16
	s_addc_u32 s1, s59, 0
	v_fma_f32 v82, v215, v184, v185
	v_fma_f32 v215, v82, v187, v80
	global_load_dwordx4 v[140:143], v200, s[0:1]
	global_load_dwordx4 v[144:147], v202, s[0:1]
	v_lshl_add_u64 v[80:81], v[204:205], 0, s[16:17]
	global_load_dwordx4 v[148:151], v[80:81], off
	s_add_i32 s7, s7, 2
	s_add_i32 s51, s51, 0x8000
	s_cmpk_gt_u32 s64, 0x81
	s_waitcnt lgkmcnt(0)
	s_barrier
	s_cbranch_scc1 .LBB0_1204

; #define SBAR() __builtin_amdgcn_sched_barrier(0)
; #define PK4(P, BASE, OUT) do { u32x4 w = {cvtpk_a(P[BASE + 0], P[BASE + 1]), cvtpk_a(P[BASE + 2], P[BASE + 3]), cvtpk_a(P[BASE + 4], P[BASE + 5]), cvtpk_a(P[BASE + 6], P[BASE + 7])}; \
;     OUT = *reinterpret_cast<bf16x8*>(&w); } while (0)
; #define SWAIT() asm volatile("s_waitcnt vmcnt(3)" ::: "memory")
; __device__ __forceinline__ float exp_pack(f32x16& p0, f32x16& p1, bf16x8& pa0, bf16x8& pa1, bf16x8& pa2, bf16x8& pa3) {
; #pragma unroll
;     for (int r = 0; r < 16; ++r) p0[r] = __builtin_amdgcn_exp2f(p0[r]);
; #pragma unroll
;     for (int r = 0; r < 16; ++r) p1[r] = __builtin_amdgcn_exp2f(p1[r]);
;     SBAR(); asm volatile("s_nop 1" ::: "memory"); SBAR();
;     ...
;     PK4(p0, 0, pa0); PK4(p0, 8, pa1); PK4(p1, 0, pa2); PK4(p1, 8, pa3);
;     ...
;     float ps0 = p0[0], ps1 = p1[0];
; #pragma unroll
;     for (int r = 1; r < 16; ++r) { ps0 += p0[r]; ps1 += p1[r]; }
;     float ps = ps0 + ps1;
;     { auto rr = __builtin_amdgcn_permlane32_swap(__float_as_uint(ps), __float_as_uint(ps), false, false);
;       ps = __uint_as_float(rr[0]) + __uint_as_float(rr[1]); }
;     return ps;
; template <bool MLA>
; __device__ __forceinline__ void attn_core(const bf16_t* __restrict__ Qb, const bf16_t* __restrict__ Kh, const bf16_t* __restrict__ Vh, int seq, char* lds,
;                                           f32x16 (&o)[Cfg<MLA>::NCB], const int wid  , const int g  ) {
;     ...
;         SWAIT(); if (j + 2 < NT) SWRITE(((j + 2) % 3) * SHM_K, ((j + 2) & 3) * SHM_V, SE);
.LBB0_1193:
	v_exp_f32_e32 v96, v96
	v_exp_f32_e32 v97, v97
	v_exp_f32_e32 v98, v98
	v_exp_f32_e32 v99, v99
	v_exp_f32_e32 v100, v100
	v_exp_f32_e32 v101, v101
	v_exp_f32_e32 v102, v102
	v_exp_f32_e32 v103, v103
	v_exp_f32_e32 v104, v104
	v_exp_f32_e32 v105, v105
	v_exp_f32_e32 v106, v106
	v_exp_f32_e32 v107, v107
	v_exp_f32_e32 v108, v108
	v_exp_f32_e32 v109, v109
	v_exp_f32_e32 v110, v110
	v_exp_f32_e32 v111, v111
	v_exp_f32_e32 v80, v80
	v_exp_f32_e32 v81, v81
	v_exp_f32_e32 v82, v82
	v_exp_f32_e32 v83, v83
	v_exp_f32_e32 v84, v84
	v_exp_f32_e32 v85, v85
	v_exp_f32_e32 v86, v86
	v_exp_f32_e32 v87, v87
	v_exp_f32_e32 v88, v88
	v_exp_f32_e32 v89, v89
	v_exp_f32_e32 v90, v90
	v_exp_f32_e32 v91, v91
	v_exp_f32_e32 v92, v92
	v_exp_f32_e32 v93, v93
	v_exp_f32_e32 v94, v94
	v_exp_f32_e32 v95, v95
	s_nop 1
	v_cvt_pk_bf16_f32 v180, v96, v97
	v_cvt_pk_bf16_f32 v181, v98, v99
	v_cvt_pk_bf16_f32 v182, v100, v101
	v_cvt_pk_bf16_f32 v183, v102, v103
	v_cvt_pk_bf16_f32 v176, v104, v105
	v_cvt_pk_bf16_f32 v177, v106, v107
	v_cvt_pk_bf16_f32 v178, v108, v109
	v_cvt_pk_bf16_f32 v179, v110, v111
	v_cvt_pk_bf16_f32 v172, v80, v81
	v_add_f32_e32 v96, v96, v97
	v_add_f32_e32 v80, v80, v81
	v_add_f32_e32 v81, v98, v96
	v_add_f32_e32 v80, v82, v80
	v_add_f32_e32 v81, v99, v81
	v_add_f32_e32 v80, v83, v80
	v_add_f32_e32 v81, v100, v81
	v_add_f32_e32 v80, v84, v80
	v_add_f32_e32 v81, v101, v81
	v_add_f32_e32 v80, v85, v80
	v_add_f32_e32 v81, v102, v81
	v_add_f32_e32 v80, v86, v80
	v_add_f32_e32 v81, v103, v81
	v_add_f32_e32 v80, v87, v80
	v_add_f32_e32 v81, v104, v81
	v_add_f32_e32 v80, v88, v80
	v_add_f32_e32 v81, v105, v81
	v_add_f32_e32 v80, v89, v80
	v_add_f32_e32 v81, v106, v81
	v_add_f32_e32 v80, v90, v80
	v_add_f32_e32 v81, v107, v81
	v_add_f32_e32 v80, v91, v80
	v_add_f32_e32 v81, v108, v81
	v_add_f32_e32 v80, v92, v80
	v_add_f32_e32 v81, v109, v81
	v_add_f32_e32 v80, v93, v80
	v_add_f32_e32 v81, v110, v81
	v_add_f32_e32 v80, v94, v80
	v_add_f32_e32 v81, v111, v81
	v_add_f32_e32 v80, v95, v80
	v_cvt_pk_bf16_f32 v173, v82, v83
	v_cvt_pk_bf16_f32 v174, v84, v85
	v_cvt_pk_bf16_f32 v175, v86, v87
	v_cvt_pk_bf16_f32 v168, v88, v89
	v_cvt_pk_bf16_f32 v169, v90, v91
	v_cvt_pk_bf16_f32 v170, v92, v93
	v_cvt_pk_bf16_f32 v171, v94, v95
	v_add_f32_e32 v185, v80, v81
	s_waitcnt vmcnt(3)
	s_cmpk_gt_u32 s64, 0x81
	s_cbranch_scc1 .LBB0_1195
	s_add_i32 s0, s51, 0x8000
	s_and_b32 s0, s0, 0x8000
	s_add_i32 s0, s0, 0
	v_add_u32_e32 v80, s0, v210
	s_waitcnt vmcnt(5)
	ds_write_b128 v80, v[132:135]
	v_add_u32_e32 v80, s0, v211
	s_add_i32 s0, s7, 0xffff
	s_mul_i32 s1, s0, 0xab
	s_bfe_u32 s1, s1, 0x70009
	s_mul_i32 s1, s1, 3
	s_sub_i32 s0, s0, s1
	s_and_b32 s0, s0, 0xff
	s_mulk_i32 s0, 0x2400
	s_waitcnt vmcnt(4)
	ds_write_b128 v80, v[128:131]
	v_add_u32_e32 v80, s0, v212
	s_waitcnt vmcnt(3)
	ds_write_b128 v80, v[136:139]
; __device__ __forceinline__ float max3f(float a, float b, float c) { return __builtin_fmaxf(__builtin_fmaxf(a, b), c); }
; __device__ __forceinline__ void rowmax_adjust(f32x16& p0, f32x16& p1, float& m2, f32x16& negm, float& alpha, const bool first) {
;     ...
;     float pmax = max3f(p0[0], p0[1], p0[2]);
; #pragma unroll
;     for (int r = 3; r < 15; r += 2) pmax = max3f(pmax, p0[r], p0[r + 1]);
;     pmax = max3f(pmax, p0[15], p1[0]);
; #pragma unroll
;     for (int r = 1; r < 15; r += 2) pmax = max3f(pmax, p1[r], p1[r + 1]);
;     pmax = fmaxf(pmax, p1[15]);
;     { auto rr = __builtin_amdgcn_permlane32_swap(__float_as_uint(pmax), __float_as_uint(pmax), false, false);
;       pmax = fmaxf(__uint_as_float(rr[0]), __uint_as_float(rr[1])); }
;     if (!first && __builtin_expect(__all(pmax <= THR2), 1)) { alpha = 1.f; }
.LBB0_1195:
	s_min_u32 s0, s64, 0x7f
	s_lshl_b32 s0, s0, 16
	s_add_i32 s16, s0, 0x40000
	s_add_u32 s0, s58, s16
	s_addc_u32 s1, s59, 0
	global_load_dwordx4 v[132:135], v200, s[0:1]
	global_load_dwordx4 v[128:131], v202, s[0:1]
	v_lshl_add_u64 v[80:81], v[204:205], 0, s[16:17]
	global_load_dwordx4 v[136:139], v[80:81], off
	s_waitcnt lgkmcnt(0)
	s_barrier
	s_or_b32 s0, s64, 1
	s_and_b32 s1, s0, 0xff
	s_mulk_i32 s1, 0xab
	s_bfe_u32 s1, s1, 0x70009
	s_mul_i32 s1, s1, 3
	s_sub_i32 s0, s0, s1
	s_and_b32 s0, s0, 0xff
	s_mulk_i32 s0, 0x2400
	v_add_u32_e32 v84, s0, v218
	s_and_b32 s0, s51, 0x8000
	v_add_u32_e32 v187, s0, v217
	ds_read_b128 v[80:83], v84
	ds_read_b128 v[192:195], v84 offset:4608
	ds_read_b128 v[188:191], v84 offset:32
	ds_read_b128 v[196:199], v84 offset:4640
	ds_read_b128 v[220:223], v84 offset:64
	ds_read_b128 v[228:231], v84 offset:4672
	ds_read_b128 v[224:227], v84 offset:96
	ds_read_b128 v[232:235], v84 offset:4704
	ds_read_b64_tr_b16 v[164:165], v187 offset:0
	ds_read_b64_tr_b16 v[166:167], v187 offset:0x800
	ds_read_b64_tr_b16 v[160:161], v187 offset:0x1000
	ds_read_b64_tr_b16 v[162:163], v187 offset:0x1800
	ds_read_b64_tr_b16 v[156:157], v187 offset:0x2000
	ds_read_b64_tr_b16 v[158:159], v187 offset:0x2800
	ds_read_b64_tr_b16 v[152:153], v187 offset:0x3000
	ds_read_b64_tr_b16 v[154:155], v187 offset:0x3800
	s_waitcnt lgkmcnt(15)
	v_mfma_f32_32x32x16_bf16 v[96:111], v[80:83], v[112:115], v[64:79]
	s_waitcnt lgkmcnt(14)
	v_mfma_f32_32x32x16_bf16 v[80:95], v[192:195], v[112:115], v[64:79]
	s_waitcnt lgkmcnt(13)
	v_mfma_f32_32x32x16_bf16 v[96:111], v[188:191], v[116:119], v[96:111]
	s_waitcnt lgkmcnt(12)
	v_mfma_f32_32x32x16_bf16 v[80:95], v[196:199], v[116:119], v[80:95]
	s_waitcnt lgkmcnt(8)
	ds_read_b64_tr_b16 v[188:189], v187 offset:0x200
	ds_read_b64_tr_b16 v[190:191], v187 offset:0xa00
	ds_read_b64_tr_b16 v[192:193], v187 offset:0x1200
	ds_read_b64_tr_b16 v[194:195], v187 offset:0x1a00
	ds_read_b64_tr_b16 v[196:197], v187 offset:0x2200
	ds_read_b64_tr_b16 v[198:199], v187 offset:0x2a00
	ds_read_b64_tr_b16 v[236:237], v187 offset:0x3200
	ds_read_b64_tr_b16 v[238:239], v187 offset:0x3a00
	v_mfma_f32_32x32x16_bf16 v[96:111], v[220:223], v[120:123], v[96:111]
	v_mfma_f32_32x32x16_bf16 v[80:95], v[228:231], v[120:123], v[80:95]
	v_mfma_f32_32x32x16_bf16 v[96:111], v[224:227], v[124:127], v[96:111]
	v_mfma_f32_32x32x16_bf16 v[80:95], v[232:235], v[124:127], v[80:95]
	ds_read_b64_tr_b16 v[220:221], v187 offset:0x600
	ds_read_b64_tr_b16 v[222:223], v187 offset:0xe00
	ds_read_b64_tr_b16 v[224:225], v187 offset:0x1600
	ds_read_b64_tr_b16 v[226:227], v187 offset:0x1e00
	ds_read_b64_tr_b16 v[228:229], v187 offset:0x2600
	ds_read_b64_tr_b16 v[230:231], v187 offset:0x2e00
	ds_read_b64_tr_b16 v[232:233], v187 offset:0x3600
	ds_read_b64_tr_b16 v[234:235], v187 offset:0x3e00
	s_waitcnt lgkmcnt(15)
	v_mfma_f32_32x32x16_bf16 v[48:63], v[180:183], v[164:167], v[48:63]
	v_mfma_f32_32x32x16_bf16 v[48:63], v[176:179], v[160:163], v[48:63]
	v_mfma_f32_32x32x16_bf16 v[48:63], v[172:175], v[156:159], v[48:63]
	v_mfma_f32_32x32x16_bf16 v[48:63], v[168:171], v[152:155], v[48:63]
	ds_read_b64_tr_b16 v[164:165], v187 offset:0x400
	ds_read_b64_tr_b16 v[166:167], v187 offset:0xc00
	ds_read_b64_tr_b16 v[160:161], v187 offset:0x1400
	ds_read_b64_tr_b16 v[162:163], v187 offset:0x1c00
	ds_read_b64_tr_b16 v[156:157], v187 offset:0x2400
	ds_read_b64_tr_b16 v[158:159], v187 offset:0x2c00
	ds_read_b64_tr_b16 v[152:153], v187 offset:0x3400
	ds_read_b64_tr_b16 v[154:155], v187 offset:0x3c00
	s_waitcnt lgkmcnt(15)
	v_mfma_f32_32x32x16_bf16 v[32:47], v[180:183], v[188:191], v[32:47]
	v_mfma_f32_32x32x16_bf16 v[32:47], v[176:179], v[192:195], v[32:47]
	v_mfma_f32_32x32x16_bf16 v[32:47], v[172:175], v[196:199], v[32:47]
	v_mfma_f32_32x32x16_bf16 v[32:47], v[168:171], v[236:239], v[32:47]
	s_waitcnt lgkmcnt(8)
	v_mfma_f32_32x32x16_bf16 v[0:15], v[180:183], v[220:223], v[0:15]
	v_mfma_f32_32x32x16_bf16 v[0:15], v[176:179], v[224:227], v[0:15]
	v_mfma_f32_32x32x16_bf16 v[0:15], v[172:175], v[228:231], v[0:15]
	v_mfma_f32_32x32x16_bf16 v[0:15], v[168:171], v[232:235], v[0:15]
	s_waitcnt lgkmcnt(0)
	v_mfma_f32_32x32x16_bf16 v[16:31], v[180:183], v[164:167], v[16:31]
	v_mfma_f32_32x32x16_bf16 v[16:31], v[176:179], v[160:163], v[16:31]
	v_mfma_f32_32x32x16_bf16 v[16:31], v[172:175], v[156:159], v[16:31]
	v_mfma_f32_32x32x16_bf16 v[16:31], v[168:171], v[152:155], v[16:31]
	s_barrier
	v_max3_f32 v168, v96, v97, v98
	v_max3_f32 v169, v81, v82, v83
	v_max3_f32 v168, v168, v99, v100
	v_max3_f32 v169, v169, v84, v85
	v_max3_f32 v168, v168, v101, v102
	v_max3_f32 v169, v169, v86, v87
	v_max3_f32 v168, v168, v103, v104
	v_max3_f32 v169, v169, v88, v89
	v_max3_f32 v168, v168, v105, v106
	v_max3_f32 v169, v169, v90, v91
	v_max3_f32 v168, v168, v107, v108
	v_max3_f32 v169, v169, v92, v93
	v_max3_f32 v168, v168, v109, v110
	v_max3_f32 v169, v169, v94, v95
	v_max3_f32 v168, v168, v111, v80
	v_max_f32_e32 v168, v168, v169
	v_mov_b32_e32 v169, v168
	s_nop 1
	v_permlane32_swap_b32_e32 v168, v169
	v_max_f32_e32 v168, v168, v169
	v_cmp_ge_f32_e32 vcc, s83, v168
	v_mov_b32_e32 v187, 1.0
	s_cmp_eq_u64 vcc, exec
	s_cbranch_scc1 .LBB0_1200
	s_branch .LBB0_1202

; #define SBAR() __builtin_amdgcn_sched_barrier(0)
; #define PK4(P, BASE, OUT) do { u32x4 w = {cvtpk_a(P[BASE + 0], P[BASE + 1]), cvtpk_a(P[BASE + 2], P[BASE + 3]), cvtpk_a(P[BASE + 4], P[BASE + 5]), cvtpk_a(P[BASE + 6], P[BASE + 7])}; \
;     OUT = *reinterpret_cast<bf16x8*>(&w); } while (0)
; #define SWAIT() asm volatile("s_waitcnt vmcnt(3)" ::: "memory")
; __device__ __forceinline__ float exp_pack(f32x16& p0, f32x16& p1, bf16x8& pa0, bf16x8& pa1, bf16x8& pa2, bf16x8& pa3) {
; #pragma unroll
;     for (int r = 0; r < 16; ++r) p0[r] = __builtin_amdgcn_exp2f(p0[r]);
; #pragma unroll
;     for (int r = 0; r < 16; ++r) p1[r] = __builtin_amdgcn_exp2f(p1[r]);
;     SBAR(); asm volatile("s_nop 1" ::: "memory"); SBAR();
;     ...
;     PK4(p0, 0, pa0); PK4(p0, 8, pa1); PK4(p1, 0, pa2); PK4(p1, 8, pa3);
;     ...
;     float ps0 = p0[0], ps1 = p1[0];
; #pragma unroll
;     for (int r = 1; r < 16; ++r) { ps0 += p0[r]; ps1 += p1[r]; }
;     float ps = ps0 + ps1;
;     { auto rr = __builtin_amdgcn_permlane32_swap(__float_as_uint(ps), __float_as_uint(ps), false, false);
;       ps = __uint_as_float(rr[0]) + __uint_as_float(rr[1]); }
;     return ps;
; template <bool MLA>
; __device__ __forceinline__ void attn_core(const bf16_t* __restrict__ Qb, const bf16_t* __restrict__ Kh, const bf16_t* __restrict__ Vh, int seq, char* lds,
;                                           f32x16 (&o)[Cfg<MLA>::NCB], const int wid  , const int g  ) {
;     ...
;         SWAIT(); if (j + 3 < NT) SWRITE(((j + 3) % 3) * SHM_K, ((j + 3) & 3) * SHM_V, SO);
.LBB0_1200:
	v_exp_f32_e32 v80, v80
	v_exp_f32_e32 v81, v81
	v_exp_f32_e32 v96, v96
	v_exp_f32_e32 v97, v97
	v_exp_f32_e32 v98, v98
	v_exp_f32_e32 v99, v99
	v_exp_f32_e32 v100, v100
	v_exp_f32_e32 v101, v101
	v_exp_f32_e32 v102, v102
	v_exp_f32_e32 v103, v103
	v_exp_f32_e32 v104, v104
	v_exp_f32_e32 v105, v105
	v_exp_f32_e32 v106, v106
	v_exp_f32_e32 v107, v107
	v_exp_f32_e32 v108, v108
	v_exp_f32_e32 v109, v109
	v_exp_f32_e32 v110, v110
	v_exp_f32_e32 v111, v111
	v_exp_f32_e32 v82, v82
	v_exp_f32_e32 v83, v83
	v_exp_f32_e32 v84, v84
	v_exp_f32_e32 v85, v85
	v_exp_f32_e32 v86, v86
	v_exp_f32_e32 v87, v87
	v_exp_f32_e32 v88, v88
	v_exp_f32_e32 v89, v89
	v_exp_f32_e32 v90, v90
	v_exp_f32_e32 v91, v91
	v_exp_f32_e32 v92, v92
	v_exp_f32_e32 v93, v93
	v_exp_f32_e32 v94, v94
	v_exp_f32_e32 v95, v95
	s_nop 1
	v_cvt_pk_bf16_f32 v180, v96, v97
	v_cvt_pk_bf16_f32 v181, v98, v99
	v_cvt_pk_bf16_f32 v182, v100, v101
	v_cvt_pk_bf16_f32 v183, v102, v103
	v_cvt_pk_bf16_f32 v176, v104, v105
	v_cvt_pk_bf16_f32 v177, v106, v107
	v_cvt_pk_bf16_f32 v178, v108, v109
	v_cvt_pk_bf16_f32 v179, v110, v111
	v_cvt_pk_bf16_f32 v172, v80, v81
	v_add_f32_e32 v96, v96, v97
	v_add_f32_e32 v80, v80, v81
	v_add_f32_e32 v81, v98, v96
	v_add_f32_e32 v80, v82, v80
	v_add_f32_e32 v81, v99, v81
	v_add_f32_e32 v80, v83, v80
	v_add_f32_e32 v81, v100, v81
	v_add_f32_e32 v80, v84, v80
	v_add_f32_e32 v81, v101, v81
	v_add_f32_e32 v80, v85, v80
	v_add_f32_e32 v81, v102, v81
	v_add_f32_e32 v80, v86, v80
	v_add_f32_e32 v81, v103, v81
	v_add_f32_e32 v80, v87, v80
	v_add_f32_e32 v81, v104, v81
	v_add_f32_e32 v80, v88, v80
	v_add_f32_e32 v81, v105, v81
	v_add_f32_e32 v80, v89, v80
	v_add_f32_e32 v81, v106, v81
	v_add_f32_e32 v80, v90, v80
	v_add_f32_e32 v81, v107, v81
	v_add_f32_e32 v80, v91, v80
	v_add_f32_e32 v81, v108, v81
	v_add_f32_e32 v80, v92, v80
	v_add_f32_e32 v81, v109, v81
	v_add_f32_e32 v80, v93, v80
	v_add_f32_e32 v81, v110, v81
	v_add_f32_e32 v80, v94, v80
	v_add_f32_e32 v81, v111, v81
	v_add_f32_e32 v80, v95, v80
	v_cvt_pk_bf16_f32 v173, v82, v83
	v_cvt_pk_bf16_f32 v174, v84, v85
	v_cvt_pk_bf16_f32 v175, v86, v87
	v_cvt_pk_bf16_f32 v168, v88, v89
	v_cvt_pk_bf16_f32 v169, v90, v91
	v_cvt_pk_bf16_f32 v170, v92, v93
	v_cvt_pk_bf16_f32 v171, v94, v95
	v_add_f32_e32 v80, v80, v81
	s_waitcnt vmcnt(3)
	s_cmpk_gt_u32 s64, 0x80
	s_cbranch_scc1 .LBB0_1180
	s_add_i32 s0, s65, 0
	v_add_u32_e32 v82, s0, v210
	s_waitcnt vmcnt(5)
	ds_write_b128 v82, v[140:143]
	v_add_u32_e32 v82, s0, v211
	s_mul_i32 s0, s7, 0xab
	s_bfe_u32 s0, s0, 0x70009
	s_mul_i32 s0, s0, 3
	s_sub_i32 s0, s7, s0
	s_and_b32 s0, s0, 0xff
	s_mulk_i32 s0, 0x2400
	s_waitcnt vmcnt(4)
	ds_write_b128 v82, v[144:147]
	v_add_u32_e32 v82, s0, v212
	s_waitcnt vmcnt(3)
	ds_write_b128 v82, v[148:151]
	s_branch .LBB0_1180

; #define SBAR() __builtin_amdgcn_sched_barrier(0)
; __device__ __forceinline__ int crow(int r, int hi) { return (r & 3) + 8 * (r >> 2) + 4 * hi; }
; template <bool MLA>
; __device__ __forceinline__ void attn_core(const bf16_t* __restrict__ Qb, const bf16_t* __restrict__ Kh, const bf16_t* __restrict__ Vh, int seq, char* lds,
;                                           f32x16 (&o)[Cfg<MLA>::NCB], const int wid  , const int g  ) {
;     ...
;     asm volatile("s_waitcnt vmcnt(0)" ::: "memory");
;     if (hi == 0) li_l[r32] = l_reg; asm volatile("s_waitcnt lgkmcnt(0)" ::: "memory");
; #pragma unroll
;     for (int r = 0; r < 16; ++r) { const float rl = __builtin_amdgcn_rcpf(li_l[crow(r, hi)]);
; #pragma unroll
;         for (int d = 0; d < NCB; ++d) o[d][r] *= rl; }
; __global__ void __launch_bounds__(512, 2) fwd_mega(Args a) {
;     ...
;                 LANE_TID
;                 const int r32 = lane & 31, hi = lane >> 5;
;                 unsigned* stash = (unsigned*)(lds + 95232 + wave * 8192) + lane;
; #pragma unroll
;                 for (int d0 = 0; d0 < 4; ++d0)
; #pragma unroll
;                     for (int r = 0; r < 16; r += 2) { const unsigned w = stash[(d0 * 8 + (r >> 1)) * 64];
;                         o[d0][r] = bflo(w) - lam * o[d0][r]; o[d0][r + 1] = bfhi(w) - lam * o[d0][r + 1]; }
;                 asm volatile("s_waitcnt lgkmcnt(0)" ::: "memory"); SBAR();
;                 char* T = (char*)lds + 95232 + wave * 8192; char* tw = T + hi * 1024 + r32 * 2;
.LBB0_1206:
	s_waitcnt vmcnt(0)
	s_mov_b64 s[10:11], s[52:53]
	v_mov_b32_e32 v80, v215
	s_nop 1
	v_permlane32_swap_b32_e32 v215, v80
	v_add_f32_e32 v215, v215, v80
	s_and_saveexec_b64 s[0:1], s[4:5]
	ds_write_b32 v214, v215
	s_or_b64 exec, exec, s[0:1]
	s_waitcnt lgkmcnt(0)
	v_add_u32_e32 v76, s42, v213
	ds_read_b128 v[68:71], v76
	ds_read_b128 v[72:75], v76 offset:32
	s_waitcnt lgkmcnt(1)
	v_rcp_f32_e32 v64, v68
	v_rcp_f32_e32 v65, v69
	v_mul_f32_e32 v67, v64, v48
	v_mul_f32_e32 v48, v64, v32
	v_mul_f32_e32 v68, v65, v49
	v_rcp_f32_e32 v32, v70
	v_mul_f32_e32 v49, v65, v33
	v_rcp_f32_e32 v33, v71
	v_mul_f32_e32 v16, v64, v16
	v_mul_f32_e32 v69, v32, v50
	v_mul_f32_e32 v50, v32, v34
	v_mul_f32_e32 v18, v32, v18
	v_mul_f32_e32 v2, v32, v2
	s_waitcnt lgkmcnt(0)
	v_rcp_f32_e32 v34, v72
	v_mul_f32_e32 v32, v33, v19
	v_rcp_f32_e32 v19, v73
	v_mul_f32_e32 v0, v64, v0
	v_mul_f32_e32 v17, v65, v17
	v_mul_f32_e32 v1, v65, v1
	v_mul_f32_e32 v64, v33, v35
	v_mul_f32_e32 v78, v34, v52
	v_mul_f32_e32 v65, v34, v36
	v_mul_f32_e32 v20, v34, v20
	v_mul_f32_e32 v4, v34, v4
	v_mul_f32_e32 v66, v19, v37
	ds_read_b128 v[34:37], v76 offset:64
	ds_read_b128 v[70:73], v76 offset:96
	v_mul_f32_e32 v77, v33, v51
	v_mul_f32_e32 v3, v33, v3
	v_mul_f32_e32 v79, v19, v53
	v_rcp_f32_e32 v51, v74
	v_mul_f32_e32 v33, v19, v21
	v_mul_f32_e32 v5, v19, v5
	v_rcp_f32_e32 v19, v75
	s_waitcnt lgkmcnt(1)
	v_rcp_f32_e32 v21, v34
	v_mul_f32_e32 v74, v51, v54
	v_mul_f32_e32 v54, v51, v38
	v_mul_f32_e32 v22, v51, v22
	v_mul_f32_e32 v6, v51, v6
	v_mul_f32_e32 v55, v19, v55
	v_mul_f32_e32 v75, v19, v39
	v_mul_f32_e32 v51, v19, v23
	v_mul_f32_e32 v7, v19, v7
	v_mul_f32_e32 v19, v21, v8
	v_rcp_f32_e32 v8, v36
	v_mul_f32_e32 v23, v21, v56
	v_mul_f32_e32 v76, v21, v40
	v_mul_f32_e32 v52, v21, v24
	v_mul_f32_e32 v81, v8, v58
	v_rcp_f32_e32 v21, v37
	v_mul_f32_e32 v82, v8, v42
	v_mul_f32_e32 v42, v8, v26
	v_mul_f32_e32 v10, v8, v10
	s_waitcnt lgkmcnt(0)
	v_rcp_f32_e32 v8, v70
	v_mul_f32_e32 v83, v21, v59
	v_mul_f32_e32 v70, v21, v43
	v_mul_f32_e32 v53, v21, v27
	v_mul_f32_e32 v21, v21, v11
	v_mul_f32_e32 v60, v8, v60
	v_rcp_f32_e32 v24, v71
	v_mul_f32_e32 v71, v8, v44
	v_mul_f32_e32 v43, v8, v28
	v_mul_f32_e32 v11, v8, v12
	v_rcp_f32_e32 v8, v72
	v_rcp_f32_e32 v34, v35
	v_mul_f32_e32 v28, v24, v61
	v_mul_f32_e32 v12, v24, v13
	v_mul_f32_e32 v61, v8, v62
	v_rcp_f32_e32 v26, v73
	v_mul_f32_e32 v73, v8, v46
	v_mul_f32_e32 v46, v8, v30
	v_mul_f32_e32 v13, v8, v14
	v_mbcnt_lo_u32_b32 v8, -1, 0
	v_mbcnt_hi_u32_b32 v8, -1, v8
	v_mul_f32_e32 v80, v34, v41
	v_lshl_add_u32 v37, v8, 2, s43
	v_mul_f32_e32 v41, v34, v25
	v_mul_f32_e32 v72, v24, v45
	v_mul_f32_e32 v44, v24, v29
	ds_read2st64_b32 v[24:25], v37 offset1:1
	v_mul_f32_e32 v14, v26, v15
	v_mul_f32_e32 v35, v34, v57
	v_mul_f32_e32 v45, v26, v31
	ds_read2st64_b32 v[30:31], v37 offset0:2 offset1:3
	ds_read2st64_b32 v[56:57], v37 offset0:4 offset1:5
	ds_read2st64_b32 v[58:59], v37 offset0:6 offset1:7
	s_waitcnt lgkmcnt(3)
	v_lshlrev_b32_e32 v15, 16, v24
	v_fma_f32 v40, -v206, v67, v15
	v_and_b32_e32 v15, 0xffff0000, v24
	v_fma_f32 v39, -v206, v68, v15
	v_lshlrev_b32_e32 v15, 16, v25
	v_fma_f32 v38, -v206, v69, v15
	v_and_b32_e32 v15, 0xffff0000, v25
	v_fma_f32 v36, -v206, v77, v15
	s_waitcnt lgkmcnt(2)
	v_lshlrev_b32_e32 v15, 16, v30
	v_mul_f32_e32 v9, v34, v9
	v_fma_f32 v34, -v206, v78, v15
	v_and_b32_e32 v15, 0xffff0000, v30
	v_fma_f32 v29, -v206, v79, v15
	v_lshlrev_b32_e32 v15, 16, v31
	v_fma_f32 v27, -v206, v74, v15
	v_and_b32_e32 v15, 0xffff0000, v31
	v_mul_f32_e32 v62, v26, v63
	v_mul_f32_e32 v84, v26, v47
	v_fma_f32 v26, -v206, v55, v15
	s_waitcnt lgkmcnt(1)
	v_lshlrev_b32_e32 v15, 16, v56
	v_fma_f32 v25, -v206, v23, v15
	v_and_b32_e32 v15, 0xffff0000, v56
	v_fma_f32 v24, -v206, v35, v15
	v_lshlrev_b32_e32 v15, 16, v57
	v_fma_f32 v23, -v206, v81, v15
	v_and_b32_e32 v15, 0xffff0000, v57
	ds_read2st64_b32 v[56:57], v37 offset0:8 offset1:9
	s_waitcnt lgkmcnt(1)
	v_lshlrev_b32_e32 v30, 16, v58
	v_fma_f32 v35, -v206, v60, v30
	v_and_b32_e32 v30, 0xffff0000, v58
	v_fma_f32 v31, -v206, v28, v30
	v_lshlrev_b32_e32 v28, 16, v59
	v_and_b32_e32 v30, 0xffff0000, v59
	s_waitcnt lgkmcnt(0)
	v_lshlrev_b32_e32 v47, 16, v56
	v_fma_f32 v28, -v206, v61, v28
	v_fma_f32 v30, -v206, v62, v30
	ds_read2st64_b32 v[58:59], v37 offset0:10 offset1:11
	ds_read2st64_b32 v[60:61], v37 offset0:12 offset1:13
	ds_read2st64_b32 v[62:63], v37 offset0:14 offset1:15
	v_fma_f32 v67, -v206, v48, v47
	v_and_b32_e32 v47, 0xffff0000, v56
	v_fma_f32 v68, -v206, v49, v47
	v_lshlrev_b32_e32 v47, 16, v57
	v_fma_f32 v69, -v206, v50, v47
	v_and_b32_e32 v47, 0xffff0000, v57
	v_fma_f32 v64, -v206, v64, v47
	s_waitcnt lgkmcnt(2)
	v_lshlrev_b32_e32 v47, 16, v58
	v_fma_f32 v65, -v206, v65, v47
	v_and_b32_e32 v47, 0xffff0000, v58
	v_fma_f32 v66, -v206, v66, v47
	v_lshlrev_b32_e32 v47, 16, v59
	v_fma_f32 v55, -v206, v54, v47
	v_and_b32_e32 v47, 0xffff0000, v59
	v_fma_f32 v54, -v206, v75, v47
	s_waitcnt lgkmcnt(1)
	v_lshlrev_b32_e32 v47, 16, v60
	v_fma_f32 v50, -v206, v76, v47
	v_and_b32_e32 v47, 0xffff0000, v60
	v_fma_f32 v49, -v206, v80, v47
	v_lshlrev_b32_e32 v47, 16, v61
	v_fma_f32 v48, -v206, v82, v47
	v_and_b32_e32 v47, 0xffff0000, v61
	s_waitcnt lgkmcnt(0)
	v_lshlrev_b32_e32 v56, 16, v62
	v_fma_f32 v47, -v206, v70, v47
	v_fma_f32 v70, -v206, v71, v56
	v_and_b32_e32 v56, 0xffff0000, v62
	v_fma_f32 v71, -v206, v72, v56
	v_lshlrev_b32_e32 v56, 16, v63
	v_fma_f32 v72, -v206, v73, v56
	ds_read2st64_b32 v[56:57], v37 offset0:16 offset1:17
	v_and_b32_e32 v58, 0xffff0000, v63
	v_fma_f32 v73, -v206, v84, v58
	ds_read2st64_b32 v[58:59], v37 offset0:18 offset1:19
	ds_read2st64_b32 v[60:61], v37 offset0:20 offset1:21
	ds_read2st64_b32 v[62:63], v37 offset0:22 offset1:23
	v_fma_f32 v15, -v206, v83, v15
	s_waitcnt lgkmcnt(3)
; #define SBAR() __builtin_amdgcn_sched_barrier(0)
; __device__ __forceinline__ unsigned cvtpk(float lo, float hi) { f32x2_t v = {lo, hi}; bf16x2_t b = __builtin_convertvector(v, bf16x2_t); return __builtin_bit_cast(unsigned, b); }
; __global__ void __launch_bounds__(512, 2) fwd_mega(Args a) {
;     ...
;                     for (int r = 0; r < 16; r += 2) { const unsigned w = stash[(d0 * 8 + (r >> 1)) * 64];
;                         o[d0][r] = bflo(w) - lam * o[d0][r]; o[d0][r + 1] = bfhi(w) - lam * o[d0][r + 1]; }
;                 asm volatile("s_waitcnt lgkmcnt(0)" ::: "memory"); SBAR();
;                 char* T = (char*)lds + 95232 + wave * 8192; char* tw = T + hi * 1024 + r32 * 2;
; #pragma unroll
;                 for (int r = 0; r < 16; ++r)
; #pragma unroll
;                     for (int d0 = 0; d0 < 4; ++d0) *(bf16_t*)(tw + ((r & 3) + 8 * (r >> 2)) * 256 + d0 * 64) = (bf16_t)cvtpk(o[d0][r], o[d0][r]);
	v_lshlrev_b32_e32 v74, 16, v56
	v_fma_f32 v74, -v206, v16, v74
	v_and_b32_e32 v16, 0xffff0000, v56
	v_fma_f32 v56, -v206, v17, v16
	v_lshlrev_b32_e32 v16, 16, v57
	v_fma_f32 v18, -v206, v18, v16
	v_and_b32_e32 v16, 0xffff0000, v57
	v_fma_f32 v57, -v206, v32, v16
	s_waitcnt lgkmcnt(2)
	v_lshlrev_b32_e32 v16, 16, v58
	v_fma_f32 v20, -v206, v20, v16
	v_and_b32_e32 v16, 0xffff0000, v58
	v_fma_f32 v58, -v206, v33, v16
	v_lshlrev_b32_e32 v16, 16, v59
	v_fma_f32 v22, -v206, v22, v16
	v_and_b32_e32 v16, 0xffff0000, v59
	v_fma_f32 v51, -v206, v51, v16
	s_waitcnt lgkmcnt(1)
	v_lshlrev_b32_e32 v16, 16, v60
	v_fma_f32 v52, -v206, v52, v16
	v_and_b32_e32 v16, 0xffff0000, v60
	v_fma_f32 v41, -v206, v41, v16
	v_lshlrev_b32_e32 v16, 16, v61
	v_fma_f32 v59, -v206, v42, v16
	v_and_b32_e32 v16, 0xffff0000, v61
	v_fma_f32 v53, -v206, v53, v16
	s_waitcnt lgkmcnt(0)
	v_lshlrev_b32_e32 v16, 16, v62
	v_fma_f32 v60, -v206, v43, v16
	v_and_b32_e32 v16, 0xffff0000, v62
	v_fma_f32 v61, -v206, v44, v16
	v_lshlrev_b32_e32 v16, 16, v63
	v_fma_f32 v46, -v206, v46, v16
	ds_read2st64_b32 v[16:17], v37 offset0:24 offset1:25
	v_and_b32_e32 v32, 0xffff0000, v63
	v_fma_f32 v62, -v206, v45, v32
	ds_read2st64_b32 v[32:33], v37 offset0:26 offset1:27
	ds_read2st64_b32 v[42:43], v37 offset0:28 offset1:29
	ds_read2st64_b32 v[44:45], v37 offset0:30 offset1:31
	s_waitcnt lgkmcnt(0)
	s_waitcnt lgkmcnt(3)
	v_lshlrev_b32_e32 v37, 16, v16
	v_and_b32_e32 v16, 0xffff0000, v16
	v_fma_f32 v1, -v206, v1, v16
	v_lshlrev_b32_e32 v16, 16, v17
	v_fma_f32 v2, -v206, v2, v16
	v_and_b32_e32 v16, 0xffff0000, v17
	v_fma_f32 v3, -v206, v3, v16
	s_waitcnt lgkmcnt(2)
	v_lshlrev_b32_e32 v16, 16, v32
	v_fma_f32 v4, -v206, v4, v16
	v_and_b32_e32 v16, 0xffff0000, v32
	v_fma_f32 v5, -v206, v5, v16
	v_lshlrev_b32_e32 v16, 16, v33
	v_fma_f32 v6, -v206, v6, v16
	v_and_b32_e32 v16, 0xffff0000, v33
	v_fma_f32 v7, -v206, v7, v16
	s_waitcnt lgkmcnt(1)
	v_lshlrev_b32_e32 v16, 16, v42
	v_fma_f32 v16, -v206, v19, v16
	s_waitcnt lgkmcnt(0)
	v_lshlrev_b32_e32 v19, 16, v44
	v_and_b32_e32 v17, 0xffff0000, v42
	v_fma_f32 v11, -v206, v11, v19
	v_and_b32_e32 v19, 0xffff0000, v44
	v_fma_f32 v9, -v206, v9, v17
	v_lshlrev_b32_e32 v17, 16, v43
	v_fma_f32 v12, -v206, v12, v19
	v_lshlrev_b32_e32 v19, 16, v45
	v_fma_f32 v10, -v206, v10, v17
	v_and_b32_e32 v17, 0xffff0000, v43
	v_fma_f32 v13, -v206, v13, v19
	v_and_b32_e32 v19, 0xffff0000, v45
	v_fma_f32 v0, -v206, v0, v37
	v_fma_f32 v17, -v206, v21, v17
	v_fma_f32 v14, -v206, v14, v19
	v_lshlrev_b32_e32 v19, 5, v8
	v_lshlrev_b32_e32 v21, 1, v8
	v_and_b32_e32 v19, 0xfffffc00, v19
	v_and_b32_e32 v21, 62, v21
	v_add3_u32 v19, s43, v19, v21
	v_cvt_pk_bf16_f32 v0, v0, s0
	ds_write_b16 v19, v0 offset:192
	v_cvt_pk_bf16_f32 v0, v39, s0
	ds_write_b16 v19, v0 offset:256
	v_cvt_pk_bf16_f32 v0, v68, s0
	ds_write_b16 v19, v0 offset:320
	v_cvt_pk_bf16_f32 v0, v56, s0
	ds_write_b16 v19, v0 offset:384
	v_cvt_pk_bf16_f32 v0, v1, s0
	ds_write_b16 v19, v0 offset:448
	v_cvt_pk_bf16_f32 v0, v38, s0
	ds_write_b16 v19, v0 offset:512
	v_cvt_pk_bf16_f32 v0, v69, s0
	ds_write_b16 v19, v0 offset:576
	v_cvt_pk_bf16_f32 v0, v18, s0
	ds_write_b16 v19, v0 offset:640
	v_cvt_pk_bf16_f32 v0, v2, s0
	ds_write_b16 v19, v0 offset:704
	v_cvt_pk_bf16_f32 v0, v36, s0
	ds_write_b16 v19, v0 offset:768
	v_cvt_pk_bf16_f32 v0, v64, s0
	ds_write_b16 v19, v0 offset:832
	v_cvt_pk_bf16_f32 v0, v57, s0
	ds_write_b16 v19, v0 offset:896
	v_cvt_pk_bf16_f32 v0, v3, s0
	ds_write_b16 v19, v0 offset:960
	v_cvt_pk_bf16_f32 v0, v34, s0
	ds_write_b16 v19, v0 offset:2048
	v_cvt_pk_bf16_f32 v0, v65, s0
	ds_write_b16 v19, v0 offset:2112
	v_cvt_pk_bf16_f32 v0, v20, s0
	ds_write_b16 v19, v0 offset:2176
	v_cvt_pk_bf16_f32 v0, v4, s0
	ds_write_b16 v19, v0 offset:2240
	v_cvt_pk_bf16_f32 v0, v29, s0
	ds_write_b16 v19, v0 offset:2304
	v_cvt_pk_bf16_f32 v0, v66, s0
	ds_write_b16 v19, v0 offset:2368
	v_cvt_pk_bf16_f32 v0, v58, s0
	ds_write_b16 v19, v0 offset:2432
	v_cvt_pk_bf16_f32 v0, v5, s0
	ds_write_b16 v19, v0 offset:2496
	v_cvt_pk_bf16_f32 v0, v27, s0
	ds_write_b16 v19, v0 offset:2560
	v_cvt_pk_bf16_f32 v0, v55, s0
	ds_write_b16 v19, v0 offset:2624
	v_cvt_pk_bf16_f32 v0, v22, s0
	ds_write_b16 v19, v0 offset:2688
	v_cvt_pk_bf16_f32 v0, v6, s0
	ds_write_b16 v19, v0 offset:2752
	v_cvt_pk_bf16_f32 v0, v26, s0
	ds_write_b16 v19, v0 offset:2816
	v_cvt_pk_bf16_f32 v0, v54, s0
	ds_write_b16 v19, v0 offset:2880
	v_cvt_pk_bf16_f32 v0, v51, s0
	ds_write_b16 v19, v0 offset:2944
	v_cvt_pk_bf16_f32 v0, v7, s0
	ds_write_b16 v19, v0 offset:3008
	v_cvt_pk_bf16_f32 v0, v25, s0
	ds_write_b16 v19, v0 offset:4096
	v_cvt_pk_bf16_f32 v0, v50, s0
	ds_write_b16 v19, v0 offset:4160
	v_cvt_pk_bf16_f32 v0, v52, s0
	ds_write_b16 v19, v0 offset:4224
	v_cvt_pk_bf16_f32 v0, v16, s0
	ds_write_b16 v19, v0 offset:4288
	v_cvt_pk_bf16_f32 v0, v24, s0
	ds_write_b16 v19, v0 offset:4352
	v_cvt_pk_bf16_f32 v0, v49, s0
	ds_write_b16 v19, v0 offset:4416
	v_cvt_pk_bf16_f32 v0, v41, s0
	ds_write_b16 v19, v0 offset:4480
	v_cvt_pk_bf16_f32 v0, v9, s0
	ds_write_b16 v19, v0 offset:4544
	v_cvt_pk_bf16_f32 v0, v23, s0
	ds_write_b16 v19, v0 offset:4608
	v_cvt_pk_bf16_f32 v0, v48, s0
	ds_write_b16 v19, v0 offset:4672
	v_cvt_pk_bf16_f32 v0, v59, s0
	ds_write_b16 v19, v0 offset:4736
	v_cvt_pk_bf16_f32 v0, v10, s0
	ds_write_b16 v19, v0 offset:4800
	v_cvt_pk_bf16_f32 v0, v15, s0
	ds_write_b16 v19, v0 offset:4864
	v_cvt_pk_bf16_f32 v0, v47, s0
	ds_write_b16 v19, v0 offset:4928
	v_cvt_pk_bf16_f32 v0, v53, s0
	ds_write_b16 v19, v0 offset:4992
	v_cvt_pk_bf16_f32 v0, v17, s0
	ds_write_b16 v19, v0 offset:5056
	v_cvt_pk_bf16_f32 v0, v35, s0
	ds_write_b16 v19, v0 offset:6144
	v_cvt_pk_bf16_f32 v0, v70, s0
; __device__ __forceinline__ float shflx(float v, int mask) { return __builtin_bit_cast(float, __builtin_amdgcn_ds_bpermute((lane_id_v() ^ mask) << 2, __builtin_bit_cast(int, v))); }
; __device__ __forceinline__ unsigned cvtpk(float lo, float hi) { f32x2_t v = {lo, hi}; bf16x2_t b = __builtin_convertvector(v, bf16x2_t); return __builtin_bit_cast(unsigned, b); }
; __global__ void __launch_bounds__(512, 2) fwd_mega(Args a) {
;     ...
;                     for (int d0 = 0; d0 < 4; ++d0) *(bf16_t*)(tw + ((r & 3) + 8 * (r >> 2)) * 256 + d0 * 64) = (bf16_t)cvtpk(o[d0][r], o[d0][r]);
;                 const int c16 = lane & 15;
;                 const f32x4 sw0 = *(const f32x4*)(a.subln + c16 * 8), sw1 = *(const f32x4*)(a.subln + c16 * 8 + 4);
; #pragma unroll
;                 for (int j = 0; j < 8; ++j) { const int id = j * 64 + lane, row = id >> 4;
;                     const u32x4 t = *(const u32x4*)(T + id * 16);
;                     float e[8] = {bflo(t.x), bfhi(t.x), bflo(t.y), bfhi(t.y), bflo(t.z), bfhi(t.z), bflo(t.w), bfhi(t.w)};
;                     float ss = 0.f;
; #pragma unroll
;                     for (int k = 0; k < 8; ++k) ss += e[k] * e[k];
;                     ss += shflx(ss, 1); ss += shflx(ss, 2); ss += shflx(ss, 4); ss += shflx(ss, 8);
;                     const float rs = 0.8f / sqrtf(ss * (1.f / 128.f) + 1e-5f);
;                     const size_t go = (qrow0 + wave * 32 + row) * 512 + h * 128 + c16 * 8; const u32x4 g = *(const u32x4*)(GD + go);
;                     u32x4 w; w.x = cvtpk(e[0] * rs * sw0[0] * bflo(g.x), e[1] * rs * sw0[1] * bfhi(g.x)); w.y = cvtpk(e[2] * rs * sw0[2] * bflo(g.y), e[3] * rs * sw0[3] * bfhi(g.y));
;                     w.z = cvtpk(e[4] * rs * sw1[0] * bflo(g.z), e[5] * rs * sw1[1] * bfhi(g.z)); w.w = cvtpk(e[6] * rs * sw1[2] * bflo(g.w), e[7] * rs * sw1[3] * bfhi(g.w));
;                     *(u32x4*)(XD + go) = w; }
	ds_write_b16 v19, v0 offset:6208
	v_cvt_pk_bf16_f32 v0, v60, s0
	ds_write_b16 v19, v0 offset:6272
	v_cvt_pk_bf16_f32 v0, v11, s0
	ds_write_b16 v19, v0 offset:6336
	v_cvt_pk_bf16_f32 v0, v31, s0
	ds_write_b16 v19, v0 offset:6400
	v_cvt_pk_bf16_f32 v0, v71, s0
	ds_write_b16 v19, v0 offset:6464
	v_cvt_pk_bf16_f32 v0, v61, s0
	ds_write_b16 v19, v0 offset:6528
	v_cvt_pk_bf16_f32 v0, v12, s0
	ds_write_b16 v19, v0 offset:6592
	v_cvt_pk_bf16_f32 v0, v28, s0
	ds_write_b16 v19, v0 offset:6656
	v_cvt_pk_bf16_f32 v0, v72, s0
	ds_write_b16 v19, v0 offset:6720
	v_cvt_pk_bf16_f32 v0, v46, s0
	ds_write_b16 v19, v0 offset:6784
	v_cvt_pk_bf16_f32 v0, v13, s0
	ds_write_b16 v19, v0 offset:6848
	v_cvt_pk_bf16_f32 v0, v30, s0
	ds_write_b16 v19, v0 offset:6912
	v_cvt_pk_bf16_f32 v0, v73, s0
	ds_write_b16 v19, v0 offset:6976
	v_cvt_pk_bf16_f32 v0, v62, s0
	ds_write_b16 v19, v0 offset:7040
	v_cvt_pk_bf16_f32 v0, v14, s0
	s_add_u32 s4, s2, s86
	v_ashrrev_i32_e32 v14, 4, v8
	ds_write_b16 v19, v0 offset:7104
	v_lshlrev_b32_e32 v0, 3, v8
	s_addc_u32 s5, s3, 0
	v_ashrrev_i32_e32 v15, 31, v14
	v_cvt_pk_bf16_f32 v21, v40, s0
	v_and_b32_e32 v9, 0x78, v0
	v_lshl_add_u64 v[14:15], s[4:5], 0, v[14:15]
	ds_write_b16 v19, v21
	v_cvt_pk_bf16_f32 v21, v67, s0
	v_readlane_b32 s52, v254, 2
	v_or_b32_e32 v200, s6, v9
	v_lshlrev_b64 v[14:15], 9, v[14:15]
	ds_write_b16 v19, v21 offset:64
	v_cvt_pk_bf16_f32 v21, v74, s0
	v_readlane_b32 s53, v254, 3
	v_lshl_add_u64 v[14:15], v[14:15], 0, v[200:201]
	ds_write_b16 v19, v21 offset:128
	v_lshlrev_b64 v[18:19], 1, v[14:15]
	s_mov_b64 s[52:53], s[10:11]
	v_lshlrev_b32_e32 v4, 2, v9
	v_readlane_b32 s60, v254, 10
	v_readlane_b32 s61, v254, 11
	v_lshl_add_u32 v9, v8, 4, s43
	v_lshl_add_u64 v[14:15], s[52:53], 0, v[18:19]
	s_nop 2
	global_load_dwordx4 v[0:3], v4, s[60:61] offset:16
	s_nop 0
	global_load_dwordx4 v[4:7], v4, s[60:61]
	ds_read_b128 v[10:13], v9
	v_mbcnt_lo_u32_b32 v9, -1, 0
	v_mbcnt_hi_u32_b32 v9, -1, v9
	v_mbcnt_lo_u32_b32 v32, -1, 0
	v_mbcnt_hi_u32_b32 v32, -1, v32
	v_mbcnt_lo_u32_b32 v33, -1, 0
	v_mbcnt_hi_u32_b32 v33, -1, v33
	v_mbcnt_lo_u32_b32 v34, -1, 0
	v_mbcnt_hi_u32_b32 v34, -1, v34
	global_load_dwordx4 v[14:17], v[14:15], off
	s_waitcnt lgkmcnt(0)
	v_lshlrev_b32_e32 v30, 16, v10
	v_and_b32_e32 v31, 0xffff0000, v10
	v_lshlrev_b32_e32 v26, 16, v11
	v_and_b32_e32 v27, 0xffff0000, v11
	v_pk_mul_f32 v[10:11], v[30:31], v[30:31]
	v_pk_mul_f32 v[28:29], v[26:27], v[26:27]
	v_add_f32_e32 v10, v10, v11
	v_lshlrev_b32_e32 v24, 16, v12
	v_and_b32_e32 v25, 0xffff0000, v12
	v_add_f32_e32 v10, v10, v28
	v_lshlrev_b32_e32 v20, 16, v13
	v_and_b32_e32 v21, 0xffff0000, v13
	v_pk_mul_f32 v[12:13], v[24:25], v[24:25]
	v_add_f32_e32 v10, v10, v29
	v_add_f32_e32 v10, v10, v12
	v_pk_mul_f32 v[22:23], v[20:21], v[20:21]
	v_add_f32_e32 v10, v10, v13
	v_lshlrev_b32_e32 v9, 2, v9
	v_add_f32_e32 v10, v10, v22
	v_xor_b32_e32 v9, 4, v9
	v_add_f32_e32 v10, v10, v23
	ds_bpermute_b32 v9, v9, v10
	v_lshlrev_b32_e32 v11, 2, v32
	v_xor_b32_e32 v11, 8, v11
	v_readlane_b32 s54, v254, 4
	v_readlane_b32 s55, v254, 5
	s_waitcnt lgkmcnt(0)
	v_add_f32_e32 v9, v10, v9
	ds_bpermute_b32 v10, v11, v9
	v_lshlrev_b32_e32 v11, 2, v33
	v_xor_b32_e32 v11, 16, v11
	v_readlane_b32 s56, v254, 6
	v_readlane_b32 s57, v254, 7
	s_waitcnt lgkmcnt(0)
	v_add_f32_e32 v9, v9, v10
	ds_bpermute_b32 v10, v11, v9
	v_lshlrev_b32_e32 v11, 2, v34
	v_xor_b32_e32 v11, 32, v11
	v_readlane_b32 s58, v254, 8
	v_readlane_b32 s59, v254, 9
	s_waitcnt lgkmcnt(0)
	v_add_f32_e32 v9, v9, v10
	ds_bpermute_b32 v10, v11, v9
	v_readlane_b32 s62, v254, 12
	v_readlane_b32 s63, v254, 13
	v_readlane_b32 s64, v254, 14
	v_readlane_b32 s65, v254, 15
	s_waitcnt lgkmcnt(0)
	v_add_f32_e32 v9, v9, v10
	v_fmamk_f32 v9, v9, 0x3c000000, v207
	v_mul_f32_e32 v10, 0x4f800000, v9
	v_cmp_gt_f32_e32 vcc, s87, v9
	v_readlane_b32 s66, v254, 16
	v_readlane_b32 s67, v254, 17
	v_cndmask_b32_e32 v9, v9, v10, vcc
	v_sqrt_f32_e32 v10, v9
	s_waitcnt vmcnt(0)
	v_lshlrev_b32_e32 v12, 16, v16
	v_add_u32_e32 v11, -1, v10
	v_and_b32_e32 v13, 0xffff0000, v16
	v_fma_f32 v16, -v11, v10, v9
	v_cmp_ge_f32_e64 s[0:1], 0, v16
	v_add_u32_e32 v16, 1, v10
	v_lshlrev_b32_e32 v22, 16, v15
	v_cndmask_b32_e64 v11, v10, v11, s[0:1]
	v_fma_f32 v10, -v16, v10, v9
	v_cmp_lt_f32_e64 s[0:1], 0, v10
	v_and_b32_e32 v23, 0xffff0000, v15
	s_nop 0
	v_cndmask_b32_e64 v10, v11, v16, s[0:1]
	v_mul_f32_e32 v11, 0x37800000, v10
	v_cndmask_b32_e32 v10, v10, v11, vcc
	v_cmp_class_f32_e32 vcc, v9, v208
	v_and_b32_e32 v11, 0xffff0000, v14
	s_nop 0
	v_cndmask_b32_e32 v9, v10, v9, vcc
	v_div_scale_f32 v16, s[0:1], v9, v9, s88
	v_rcp_f32_e32 v28, v16
	v_lshlrev_b32_e32 v10, 16, v14
	v_fma_f32 v14, -v16, v28, 1.0
	v_fmac_f32_e32 v28, v14, v28
	v_div_scale_f32 v14, vcc, s88, v9, s88
	v_mul_f32_e32 v15, v14, v28
	v_fma_f32 v29, -v16, v15, v14
	v_fmac_f32_e32 v15, v29, v28
	v_fma_f32 v14, -v16, v15, v14
	v_div_fmas_f32 v14, v14, v28, v15
	v_div_fixup_f32 v14, v14, v9, s88
	v_pk_mul_f32 v[28:29], v[14:15], v[30:31] op_sel_hi:[0,1]
	v_pk_mul_f32 v[26:27], v[14:15], v[26:27] op_sel_hi:[0,1]
	v_pk_mul_f32 v[28:29], v[4:5], v[28:29]
	v_pk_mul_f32 v[26:27], v[6:7], v[26:27]
	v_pk_mul_f32 v[10:11], v[28:29], v[10:11]
	v_pk_mul_f32 v[22:23], v[26:27], v[22:23]
	v_cvt_pk_bf16_f32 v10, v10, v11
	v_cvt_pk_bf16_f32 v11, v22, v23
	v_pk_mul_f32 v[22:23], v[14:15], v[24:25] op_sel_hi:[0,1]
	v_pk_mul_f32 v[14:15], v[14:15], v[20:21] op_sel_hi:[0,1]
	v_pk_mul_f32 v[22:23], v[0:1], v[22:23]
	v_pk_mul_f32 v[14:15], v[2:3], v[14:15]
	v_lshlrev_b32_e32 v16, 16, v17
	v_and_b32_e32 v17, 0xffff0000, v17
	v_pk_mul_f32 v[12:13], v[22:23], v[12:13]
	v_pk_mul_f32 v[14:15], v[14:15], v[16:17]
	v_cvt_pk_bf16_f32 v12, v12, v13
	v_cvt_pk_bf16_f32 v13, v14, v15
	v_lshl_add_u64 v[14:15], s[8:9], 0, v[18:19]
	v_add_u32_e32 v9, 64, v8
	global_store_dwordx4 v[14:15], v[10:13], off
	v_ashrrev_i32_e32 v14, 4, v9
	v_ashrrev_i32_e32 v15, 31, v14
	v_lshl_add_u64 v[14:15], s[4:5], 0, v[14:15]
	v_lshlrev_b64 v[14:15], 9, v[14:15]
	v_lshl_add_u64 v[14:15], v[14:15], 0, v[200:201]
	v_lshlrev_b64 v[18:19], 1, v[14:15]
	v_lshl_add_u32 v10, v9, 4, s43
	v_lshl_add_u64 v[14:15], s[52:53], 0, v[18:19]
	ds_read_b128 v[10:13], v10
	v_mbcnt_lo_u32_b32 v9, -1, 0
	v_mbcnt_hi_u32_b32 v9, -1, v9
	v_mbcnt_lo_u32_b32 v32, -1, 0
	v_mbcnt_hi_u32_b32 v32, -1, v32
	v_mbcnt_lo_u32_b32 v33, -1, 0
	v_mbcnt_hi_u32_b32 v33, -1, v33
	v_mbcnt_lo_u32_b32 v34, -1, 0
	v_mbcnt_hi_u32_b32 v34, -1, v34
	global_load_dwordx4 v[14:17], v[14:15], off
	s_waitcnt lgkmcnt(0)
; __device__ __forceinline__ float shflx(float v, int mask) { return __builtin_bit_cast(float, __builtin_amdgcn_ds_bpermute((lane_id_v() ^ mask) << 2, __builtin_bit_cast(int, v))); }
; __device__ __forceinline__ unsigned cvtpk(float lo, float hi) { f32x2_t v = {lo, hi}; bf16x2_t b = __builtin_convertvector(v, bf16x2_t); return __builtin_bit_cast(unsigned, b); }
; __global__ void __launch_bounds__(512, 2) fwd_mega(Args a) {
;     ...
;                 for (int j = 0; j < 8; ++j) { const int id = j * 64 + lane, row = id >> 4;
;                     const u32x4 t = *(const u32x4*)(T + id * 16);
;                     float e[8] = {bflo(t.x), bfhi(t.x), bflo(t.y), bfhi(t.y), bflo(t.z), bfhi(t.z), bflo(t.w), bfhi(t.w)};
;                     float ss = 0.f;
; #pragma unroll
;                     for (int k = 0; k < 8; ++k) ss += e[k] * e[k];
;                     ss += shflx(ss, 1); ss += shflx(ss, 2); ss += shflx(ss, 4); ss += shflx(ss, 8);
;                     const float rs = 0.8f / sqrtf(ss * (1.f / 128.f) + 1e-5f);
;                     const size_t go = (qrow0 + wave * 32 + row) * 512 + h * 128 + c16 * 8; const u32x4 g = *(const u32x4*)(GD + go);
;                     u32x4 w; w.x = cvtpk(e[0] * rs * sw0[0] * bflo(g.x), e[1] * rs * sw0[1] * bfhi(g.x)); w.y = cvtpk(e[2] * rs * sw0[2] * bflo(g.y), e[3] * rs * sw0[3] * bfhi(g.y));
;                     w.z = cvtpk(e[4] * rs * sw1[0] * bflo(g.z), e[5] * rs * sw1[1] * bfhi(g.z)); w.w = cvtpk(e[6] * rs * sw1[2] * bflo(g.w), e[7] * rs * sw1[3] * bfhi(g.w));
;                     *(u32x4*)(XD + go) = w; }
	v_lshlrev_b32_e32 v30, 16, v10
	v_and_b32_e32 v31, 0xffff0000, v10
	v_lshlrev_b32_e32 v26, 16, v11
	v_and_b32_e32 v27, 0xffff0000, v11
	v_pk_mul_f32 v[10:11], v[30:31], v[30:31]
	v_pk_mul_f32 v[28:29], v[26:27], v[26:27]
	v_add_f32_e32 v10, v10, v11
	v_lshlrev_b32_e32 v24, 16, v12
	v_and_b32_e32 v25, 0xffff0000, v12
	v_add_f32_e32 v10, v10, v28
	v_lshlrev_b32_e32 v20, 16, v13
	v_and_b32_e32 v21, 0xffff0000, v13
	v_pk_mul_f32 v[12:13], v[24:25], v[24:25]
	v_add_f32_e32 v10, v10, v29
	v_add_f32_e32 v10, v10, v12
	v_pk_mul_f32 v[22:23], v[20:21], v[20:21]
	v_add_f32_e32 v10, v10, v13
	v_lshlrev_b32_e32 v9, 2, v9
	v_add_f32_e32 v10, v10, v22
	v_xor_b32_e32 v9, 4, v9
	v_add_f32_e32 v10, v10, v23
	ds_bpermute_b32 v9, v9, v10
	v_lshlrev_b32_e32 v11, 2, v32
	v_xor_b32_e32 v11, 8, v11
	s_waitcnt lgkmcnt(0)
	v_add_f32_e32 v9, v10, v9
	ds_bpermute_b32 v10, v11, v9
	v_lshlrev_b32_e32 v11, 2, v33
	v_xor_b32_e32 v11, 16, v11
	s_waitcnt lgkmcnt(0)
	v_add_f32_e32 v9, v9, v10
	ds_bpermute_b32 v10, v11, v9
	v_lshlrev_b32_e32 v11, 2, v34
	v_xor_b32_e32 v11, 32, v11
	s_waitcnt lgkmcnt(0)
	v_add_f32_e32 v9, v9, v10
	ds_bpermute_b32 v10, v11, v9
	s_waitcnt lgkmcnt(0)
	v_add_f32_e32 v9, v9, v10
	v_fmamk_f32 v9, v9, 0x3c000000, v207
	v_mul_f32_e32 v10, 0x4f800000, v9
	v_cmp_gt_f32_e32 vcc, s87, v9
	s_waitcnt vmcnt(0)
	v_lshlrev_b32_e32 v12, 16, v16
	v_cndmask_b32_e32 v9, v9, v10, vcc
	v_sqrt_f32_e32 v10, v9
	v_and_b32_e32 v13, 0xffff0000, v16
	v_lshlrev_b32_e32 v22, 16, v15
	v_and_b32_e32 v23, 0xffff0000, v15
	v_add_u32_e32 v11, -1, v10
	v_fma_f32 v16, -v11, v10, v9
	v_cmp_ge_f32_e64 s[0:1], 0, v16
	v_add_u32_e32 v16, 1, v10
	s_nop 0
	v_cndmask_b32_e64 v11, v10, v11, s[0:1]
	v_fma_f32 v10, -v16, v10, v9
	v_cmp_lt_f32_e64 s[0:1], 0, v10
	s_nop 1
	v_cndmask_b32_e64 v10, v11, v16, s[0:1]
	v_mul_f32_e32 v11, 0x37800000, v10
	v_cndmask_b32_e32 v10, v10, v11, vcc
	v_cmp_class_f32_e32 vcc, v9, v208
	v_and_b32_e32 v11, 0xffff0000, v14
	s_nop 0
	v_cndmask_b32_e32 v9, v10, v9, vcc
	v_div_scale_f32 v16, s[0:1], v9, v9, s88
	v_rcp_f32_e32 v28, v16
	v_lshlrev_b32_e32 v10, 16, v14
	v_fma_f32 v14, -v16, v28, 1.0
	v_fmac_f32_e32 v28, v14, v28
	v_div_scale_f32 v14, vcc, s88, v9, s88
	v_mul_f32_e32 v15, v14, v28
	v_fma_f32 v29, -v16, v15, v14
	v_fmac_f32_e32 v15, v29, v28
	v_fma_f32 v14, -v16, v15, v14
	v_div_fmas_f32 v14, v14, v28, v15
	v_div_fixup_f32 v14, v14, v9, s88
	v_pk_mul_f32 v[28:29], v[14:15], v[30:31] op_sel_hi:[0,1]
	v_pk_mul_f32 v[26:27], v[14:15], v[26:27] op_sel_hi:[0,1]
	v_pk_mul_f32 v[28:29], v[4:5], v[28:29]
	v_pk_mul_f32 v[26:27], v[6:7], v[26:27]
	v_pk_mul_f32 v[10:11], v[28:29], v[10:11]
	v_pk_mul_f32 v[22:23], v[26:27], v[22:23]
	v_cvt_pk_bf16_f32 v10, v10, v11
	v_cvt_pk_bf16_f32 v11, v22, v23
	v_pk_mul_f32 v[22:23], v[14:15], v[24:25] op_sel_hi:[0,1]
	v_pk_mul_f32 v[14:15], v[14:15], v[20:21] op_sel_hi:[0,1]
	v_pk_mul_f32 v[22:23], v[0:1], v[22:23]
	v_pk_mul_f32 v[14:15], v[2:3], v[14:15]
	v_lshlrev_b32_e32 v16, 16, v17
	v_and_b32_e32 v17, 0xffff0000, v17
	v_pk_mul_f32 v[12:13], v[22:23], v[12:13]
	v_pk_mul_f32 v[14:15], v[14:15], v[16:17]
	v_cvt_pk_bf16_f32 v12, v12, v13
	v_cvt_pk_bf16_f32 v13, v14, v15
	v_lshl_add_u64 v[14:15], s[8:9], 0, v[18:19]
	v_add_u32_e32 v9, 0x80, v8
	global_store_dwordx4 v[14:15], v[10:13], off
	v_ashrrev_i32_e32 v14, 4, v9
	v_ashrrev_i32_e32 v15, 31, v14
	v_lshl_add_u64 v[14:15], s[4:5], 0, v[14:15]
	v_lshlrev_b64 v[14:15], 9, v[14:15]
	v_lshl_add_u64 v[14:15], v[14:15], 0, v[200:201]
	v_lshlrev_b64 v[18:19], 1, v[14:15]
	v_lshl_add_u32 v10, v9, 4, s43
	v_lshl_add_u64 v[14:15], s[52:53], 0, v[18:19]
	ds_read_b128 v[10:13], v10
	v_mbcnt_lo_u32_b32 v9, -1, 0
	v_mbcnt_hi_u32_b32 v9, -1, v9
	v_mbcnt_lo_u32_b32 v32, -1, 0
	v_mbcnt_hi_u32_b32 v32, -1, v32
	v_mbcnt_lo_u32_b32 v33, -1, 0
	v_mbcnt_hi_u32_b32 v33, -1, v33
	v_mbcnt_lo_u32_b32 v34, -1, 0
	v_mbcnt_hi_u32_b32 v34, -1, v34
	global_load_dwordx4 v[14:17], v[14:15], off
	s_waitcnt lgkmcnt(0)
	v_lshlrev_b32_e32 v30, 16, v10
	v_and_b32_e32 v31, 0xffff0000, v10
	v_lshlrev_b32_e32 v26, 16, v11
	v_and_b32_e32 v27, 0xffff0000, v11
	v_pk_mul_f32 v[10:11], v[30:31], v[30:31]
	v_pk_mul_f32 v[28:29], v[26:27], v[26:27]
	v_add_f32_e32 v10, v10, v11
	v_lshlrev_b32_e32 v24, 16, v12
	v_and_b32_e32 v25, 0xffff0000, v12
	v_add_f32_e32 v10, v10, v28
	v_lshlrev_b32_e32 v20, 16, v13
	v_and_b32_e32 v21, 0xffff0000, v13
	v_pk_mul_f32 v[12:13], v[24:25], v[24:25]
	v_add_f32_e32 v10, v10, v29
	v_add_f32_e32 v10, v10, v12
	v_pk_mul_f32 v[22:23], v[20:21], v[20:21]
	v_add_f32_e32 v10, v10, v13
	v_lshlrev_b32_e32 v9, 2, v9
	v_add_f32_e32 v10, v10, v22
	v_xor_b32_e32 v9, 4, v9
	v_add_f32_e32 v10, v10, v23
	ds_bpermute_b32 v9, v9, v10
	v_lshlrev_b32_e32 v11, 2, v32
	v_xor_b32_e32 v11, 8, v11
	s_waitcnt lgkmcnt(0)
	v_add_f32_e32 v9, v10, v9
	ds_bpermute_b32 v10, v11, v9
	v_lshlrev_b32_e32 v11, 2, v33
	v_xor_b32_e32 v11, 16, v11
	s_waitcnt lgkmcnt(0)
	v_add_f32_e32 v9, v9, v10
	ds_bpermute_b32 v10, v11, v9
	v_lshlrev_b32_e32 v11, 2, v34
	v_xor_b32_e32 v11, 32, v11
	s_waitcnt lgkmcnt(0)
	v_add_f32_e32 v9, v9, v10
	ds_bpermute_b32 v10, v11, v9
	s_waitcnt lgkmcnt(0)
	v_add_f32_e32 v9, v9, v10
	v_fmamk_f32 v9, v9, 0x3c000000, v207
	v_mul_f32_e32 v10, 0x4f800000, v9
	v_cmp_gt_f32_e32 vcc, s87, v9
	s_waitcnt vmcnt(0)
; __device__ __forceinline__ float shflx(float v, int mask) { return __builtin_bit_cast(float, __builtin_amdgcn_ds_bpermute((lane_id_v() ^ mask) << 2, __builtin_bit_cast(int, v))); }
; __device__ __forceinline__ unsigned cvtpk(float lo, float hi) { f32x2_t v = {lo, hi}; bf16x2_t b = __builtin_convertvector(v, bf16x2_t); return __builtin_bit_cast(unsigned, b); }
; __global__ void __launch_bounds__(512, 2) fwd_mega(Args a) {
;     ...
;                 for (int j = 0; j < 8; ++j) { const int id = j * 64 + lane, row = id >> 4;
;                     const u32x4 t = *(const u32x4*)(T + id * 16);
;                     float e[8] = {bflo(t.x), bfhi(t.x), bflo(t.y), bfhi(t.y), bflo(t.z), bfhi(t.z), bflo(t.w), bfhi(t.w)};
;                     float ss = 0.f;
; #pragma unroll
;                     for (int k = 0; k < 8; ++k) ss += e[k] * e[k];
;                     ss += shflx(ss, 1); ss += shflx(ss, 2); ss += shflx(ss, 4); ss += shflx(ss, 8);
;                     const float rs = 0.8f / sqrtf(ss * (1.f / 128.f) + 1e-5f);
;                     const size_t go = (qrow0 + wave * 32 + row) * 512 + h * 128 + c16 * 8; const u32x4 g = *(const u32x4*)(GD + go);
;                     u32x4 w; w.x = cvtpk(e[0] * rs * sw0[0] * bflo(g.x), e[1] * rs * sw0[1] * bfhi(g.x)); w.y = cvtpk(e[2] * rs * sw0[2] * bflo(g.y), e[3] * rs * sw0[3] * bfhi(g.y));
;                     w.z = cvtpk(e[4] * rs * sw1[0] * bflo(g.z), e[5] * rs * sw1[1] * bfhi(g.z)); w.w = cvtpk(e[6] * rs * sw1[2] * bflo(g.w), e[7] * rs * sw1[3] * bfhi(g.w));
;                     *(u32x4*)(XD + go) = w; }
	v_lshlrev_b32_e32 v12, 16, v16
	v_cndmask_b32_e32 v9, v9, v10, vcc
	v_sqrt_f32_e32 v10, v9
	v_and_b32_e32 v13, 0xffff0000, v16
	v_lshlrev_b32_e32 v22, 16, v15
	v_and_b32_e32 v23, 0xffff0000, v15
	v_add_u32_e32 v11, -1, v10
	v_fma_f32 v16, -v11, v10, v9
	v_cmp_ge_f32_e64 s[0:1], 0, v16
	v_add_u32_e32 v16, 1, v10
	s_nop 0
	v_cndmask_b32_e64 v11, v10, v11, s[0:1]
	v_fma_f32 v10, -v16, v10, v9
	v_cmp_lt_f32_e64 s[0:1], 0, v10
	s_nop 1
	v_cndmask_b32_e64 v10, v11, v16, s[0:1]
	v_mul_f32_e32 v11, 0x37800000, v10
	v_cndmask_b32_e32 v10, v10, v11, vcc
	v_cmp_class_f32_e32 vcc, v9, v208
	v_and_b32_e32 v11, 0xffff0000, v14
	s_nop 0
	v_cndmask_b32_e32 v9, v10, v9, vcc
	v_div_scale_f32 v16, s[0:1], v9, v9, s88
	v_rcp_f32_e32 v28, v16
	v_lshlrev_b32_e32 v10, 16, v14
	v_fma_f32 v14, -v16, v28, 1.0
	v_fmac_f32_e32 v28, v14, v28
	v_div_scale_f32 v14, vcc, s88, v9, s88
	v_mul_f32_e32 v15, v14, v28
	v_fma_f32 v29, -v16, v15, v14
	v_fmac_f32_e32 v15, v29, v28
	v_fma_f32 v14, -v16, v15, v14
	v_div_fmas_f32 v14, v14, v28, v15
	v_div_fixup_f32 v14, v14, v9, s88
	v_pk_mul_f32 v[28:29], v[14:15], v[30:31] op_sel_hi:[0,1]
	v_pk_mul_f32 v[26:27], v[14:15], v[26:27] op_sel_hi:[0,1]
	v_pk_mul_f32 v[28:29], v[4:5], v[28:29]
	v_pk_mul_f32 v[26:27], v[6:7], v[26:27]
	v_pk_mul_f32 v[10:11], v[28:29], v[10:11]
	v_pk_mul_f32 v[22:23], v[26:27], v[22:23]
	v_cvt_pk_bf16_f32 v10, v10, v11
	v_cvt_pk_bf16_f32 v11, v22, v23
	v_pk_mul_f32 v[22:23], v[14:15], v[24:25] op_sel_hi:[0,1]
	v_pk_mul_f32 v[14:15], v[14:15], v[20:21] op_sel_hi:[0,1]
	v_pk_mul_f32 v[22:23], v[0:1], v[22:23]
	v_pk_mul_f32 v[14:15], v[2:3], v[14:15]
	v_lshlrev_b32_e32 v16, 16, v17
	v_and_b32_e32 v17, 0xffff0000, v17
	v_pk_mul_f32 v[12:13], v[22:23], v[12:13]
	v_pk_mul_f32 v[14:15], v[14:15], v[16:17]
	v_cvt_pk_bf16_f32 v12, v12, v13
	v_cvt_pk_bf16_f32 v13, v14, v15
	v_lshl_add_u64 v[14:15], s[8:9], 0, v[18:19]
	v_add_u32_e32 v9, 0xc0, v8
	global_store_dwordx4 v[14:15], v[10:13], off
	v_ashrrev_i32_e32 v14, 4, v9
	v_ashrrev_i32_e32 v15, 31, v14
	v_lshl_add_u64 v[14:15], s[4:5], 0, v[14:15]
	v_lshlrev_b64 v[14:15], 9, v[14:15]
	v_lshl_add_u64 v[14:15], v[14:15], 0, v[200:201]
	v_lshlrev_b64 v[18:19], 1, v[14:15]
	v_lshl_add_u32 v10, v9, 4, s43
	v_lshl_add_u64 v[14:15], s[52:53], 0, v[18:19]
	ds_read_b128 v[10:13], v10
	v_mbcnt_lo_u32_b32 v9, -1, 0
	v_mbcnt_hi_u32_b32 v9, -1, v9
	v_mbcnt_lo_u32_b32 v32, -1, 0
	v_mbcnt_hi_u32_b32 v32, -1, v32
	v_mbcnt_lo_u32_b32 v33, -1, 0
	v_mbcnt_hi_u32_b32 v33, -1, v33
	v_mbcnt_lo_u32_b32 v34, -1, 0
	v_mbcnt_hi_u32_b32 v34, -1, v34
	global_load_dwordx4 v[14:17], v[14:15], off
	s_waitcnt lgkmcnt(0)
	v_lshlrev_b32_e32 v30, 16, v10
	v_and_b32_e32 v31, 0xffff0000, v10
	v_lshlrev_b32_e32 v26, 16, v11
	v_and_b32_e32 v27, 0xffff0000, v11
	v_pk_mul_f32 v[10:11], v[30:31], v[30:31]
	v_pk_mul_f32 v[28:29], v[26:27], v[26:27]
	v_add_f32_e32 v10, v10, v11
	v_lshlrev_b32_e32 v24, 16, v12
	v_and_b32_e32 v25, 0xffff0000, v12
	v_add_f32_e32 v10, v10, v28
	v_lshlrev_b32_e32 v20, 16, v13
	v_and_b32_e32 v21, 0xffff0000, v13
	v_pk_mul_f32 v[12:13], v[24:25], v[24:25]
	v_add_f32_e32 v10, v10, v29
	v_add_f32_e32 v10, v10, v12
	v_pk_mul_f32 v[22:23], v[20:21], v[20:21]
	v_add_f32_e32 v10, v10, v13
	v_lshlrev_b32_e32 v9, 2, v9
	v_add_f32_e32 v10, v10, v22
	v_xor_b32_e32 v9, 4, v9
	v_add_f32_e32 v10, v10, v23
	ds_bpermute_b32 v9, v9, v10
	v_lshlrev_b32_e32 v11, 2, v32
	v_xor_b32_e32 v11, 8, v11
	s_waitcnt lgkmcnt(0)
	v_add_f32_e32 v9, v10, v9
	ds_bpermute_b32 v10, v11, v9
	v_lshlrev_b32_e32 v11, 2, v33
	v_xor_b32_e32 v11, 16, v11
	s_waitcnt lgkmcnt(0)
	v_add_f32_e32 v9, v9, v10
	ds_bpermute_b32 v10, v11, v9
	v_lshlrev_b32_e32 v11, 2, v34
	v_xor_b32_e32 v11, 32, v11
	s_waitcnt lgkmcnt(0)
	v_add_f32_e32 v9, v9, v10
	ds_bpermute_b32 v10, v11, v9
	s_waitcnt lgkmcnt(0)
	v_add_f32_e32 v9, v9, v10
	v_fmamk_f32 v9, v9, 0x3c000000, v207
	v_mul_f32_e32 v10, 0x4f800000, v9
	v_cmp_gt_f32_e32 vcc, s87, v9
	s_waitcnt vmcnt(0)
	v_lshlrev_b32_e32 v12, 16, v16
	v_cndmask_b32_e32 v9, v9, v10, vcc
	v_sqrt_f32_e32 v10, v9
	v_and_b32_e32 v13, 0xffff0000, v16
	v_lshlrev_b32_e32 v22, 16, v15
	v_and_b32_e32 v23, 0xffff0000, v15
	v_add_u32_e32 v11, -1, v10
	v_fma_f32 v16, -v11, v10, v9
	v_cmp_ge_f32_e64 s[0:1], 0, v16
	v_add_u32_e32 v16, 1, v10
	s_nop 0
	v_cndmask_b32_e64 v11, v10, v11, s[0:1]
	v_fma_f32 v10, -v16, v10, v9
	v_cmp_lt_f32_e64 s[0:1], 0, v10
	s_nop 1
	v_cndmask_b32_e64 v10, v11, v16, s[0:1]
	v_mul_f32_e32 v11, 0x37800000, v10
	v_cndmask_b32_e32 v10, v10, v11, vcc
	v_cmp_class_f32_e32 vcc, v9, v208
	v_and_b32_e32 v11, 0xffff0000, v14
	s_nop 0
	v_cndmask_b32_e32 v9, v10, v9, vcc
	v_div_scale_f32 v16, s[0:1], v9, v9, s88
	v_rcp_f32_e32 v28, v16
	v_lshlrev_b32_e32 v10, 16, v14
	v_fma_f32 v14, -v16, v28, 1.0
	v_fmac_f32_e32 v28, v14, v28
	v_div_scale_f32 v14, vcc, s88, v9, s88
	v_mul_f32_e32 v15, v14, v28
	v_fma_f32 v29, -v16, v15, v14
	v_fmac_f32_e32 v15, v29, v28
	v_fma_f32 v14, -v16, v15, v14
	v_div_fmas_f32 v14, v14, v28, v15
	v_div_fixup_f32 v14, v14, v9, s88
	v_pk_mul_f32 v[28:29], v[14:15], v[30:31] op_sel_hi:[0,1]
	v_pk_mul_f32 v[26:27], v[14:15], v[26:27] op_sel_hi:[0,1]
	v_pk_mul_f32 v[28:29], v[4:5], v[28:29]
	v_pk_mul_f32 v[26:27], v[6:7], v[26:27]
	v_pk_mul_f32 v[10:11], v[28:29], v[10:11]
	v_pk_mul_f32 v[22:23], v[26:27], v[22:23]
	v_cvt_pk_bf16_f32 v10, v10, v11
	v_cvt_pk_bf16_f32 v11, v22, v23
	v_pk_mul_f32 v[22:23], v[14:15], v[24:25] op_sel_hi:[0,1]
	v_pk_mul_f32 v[14:15], v[14:15], v[20:21] op_sel_hi:[0,1]
	v_pk_mul_f32 v[22:23], v[0:1], v[22:23]
	v_pk_mul_f32 v[14:15], v[2:3], v[14:15]
	v_lshlrev_b32_e32 v16, 16, v17
	v_and_b32_e32 v17, 0xffff0000, v17
	v_pk_mul_f32 v[12:13], v[22:23], v[12:13]
	v_pk_mul_f32 v[14:15], v[14:15], v[16:17]
	v_cvt_pk_bf16_f32 v12, v12, v13
	v_cvt_pk_bf16_f32 v13, v14, v15
	v_lshl_add_u64 v[14:15], s[8:9], 0, v[18:19]
	v_add_u32_e32 v9, 0x100, v8
	global_store_dwordx4 v[14:15], v[10:13], off
	v_ashrrev_i32_e32 v14, 4, v9
	v_ashrrev_i32_e32 v15, 31, v14
	v_lshl_add_u64 v[14:15], s[4:5], 0, v[14:15]
	v_lshlrev_b64 v[14:15], 9, v[14:15]
	v_lshl_add_u64 v[14:15], v[14:15], 0, v[200:201]
	v_lshlrev_b64 v[18:19], 1, v[14:15]
	v_lshl_add_u32 v10, v9, 4, s43
	v_lshl_add_u64 v[14:15], s[52:53], 0, v[18:19]
	ds_read_b128 v[10:13], v10
	v_mbcnt_lo_u32_b32 v9, -1, 0
	v_mbcnt_hi_u32_b32 v9, -1, v9
	v_mbcnt_lo_u32_b32 v32, -1, 0
	v_mbcnt_hi_u32_b32 v32, -1, v32
	v_mbcnt_lo_u32_b32 v33, -1, 0
	v_mbcnt_hi_u32_b32 v33, -1, v33
	v_mbcnt_lo_u32_b32 v34, -1, 0
	v_mbcnt_hi_u32_b32 v34, -1, v34
	global_load_dwordx4 v[14:17], v[14:15], off
	s_waitcnt lgkmcnt(0)
; __device__ __forceinline__ float shflx(float v, int mask) { return __builtin_bit_cast(float, __builtin_amdgcn_ds_bpermute((lane_id_v() ^ mask) << 2, __builtin_bit_cast(int, v))); }
; __device__ __forceinline__ unsigned cvtpk(float lo, float hi) { f32x2_t v = {lo, hi}; bf16x2_t b = __builtin_convertvector(v, bf16x2_t); return __builtin_bit_cast(unsigned, b); }
; __global__ void __launch_bounds__(512, 2) fwd_mega(Args a) {
;     ...
;                 for (int j = 0; j < 8; ++j) { const int id = j * 64 + lane, row = id >> 4;
;                     const u32x4 t = *(const u32x4*)(T + id * 16);
;                     float e[8] = {bflo(t.x), bfhi(t.x), bflo(t.y), bfhi(t.y), bflo(t.z), bfhi(t.z), bflo(t.w), bfhi(t.w)};
;                     float ss = 0.f;
; #pragma unroll
;                     for (int k = 0; k < 8; ++k) ss += e[k] * e[k];
;                     ss += shflx(ss, 1); ss += shflx(ss, 2); ss += shflx(ss, 4); ss += shflx(ss, 8);
;                     const float rs = 0.8f / sqrtf(ss * (1.f / 128.f) + 1e-5f);
;                     const size_t go = (qrow0 + wave * 32 + row) * 512 + h * 128 + c16 * 8; const u32x4 g = *(const u32x4*)(GD + go);
;                     u32x4 w; w.x = cvtpk(e[0] * rs * sw0[0] * bflo(g.x), e[1] * rs * sw0[1] * bfhi(g.x)); w.y = cvtpk(e[2] * rs * sw0[2] * bflo(g.y), e[3] * rs * sw0[3] * bfhi(g.y));
;                     w.z = cvtpk(e[4] * rs * sw1[0] * bflo(g.z), e[5] * rs * sw1[1] * bfhi(g.z)); w.w = cvtpk(e[6] * rs * sw1[2] * bflo(g.w), e[7] * rs * sw1[3] * bfhi(g.w));
;                     *(u32x4*)(XD + go) = w; }
	v_lshlrev_b32_e32 v30, 16, v10
	v_and_b32_e32 v31, 0xffff0000, v10
	v_lshlrev_b32_e32 v26, 16, v11
	v_and_b32_e32 v27, 0xffff0000, v11
	v_pk_mul_f32 v[10:11], v[30:31], v[30:31]
	v_pk_mul_f32 v[28:29], v[26:27], v[26:27]
	v_add_f32_e32 v10, v10, v11
	v_lshlrev_b32_e32 v24, 16, v12
	v_and_b32_e32 v25, 0xffff0000, v12
	v_add_f32_e32 v10, v10, v28
	v_lshlrev_b32_e32 v20, 16, v13
	v_and_b32_e32 v21, 0xffff0000, v13
	v_pk_mul_f32 v[12:13], v[24:25], v[24:25]
	v_add_f32_e32 v10, v10, v29
	v_add_f32_e32 v10, v10, v12
	v_pk_mul_f32 v[22:23], v[20:21], v[20:21]
	v_add_f32_e32 v10, v10, v13
	v_lshlrev_b32_e32 v9, 2, v9
	v_add_f32_e32 v10, v10, v22
	v_xor_b32_e32 v9, 4, v9
	v_add_f32_e32 v10, v10, v23
	ds_bpermute_b32 v9, v9, v10
	v_lshlrev_b32_e32 v11, 2, v32
	v_xor_b32_e32 v11, 8, v11
	s_waitcnt lgkmcnt(0)
	v_add_f32_e32 v9, v10, v9
	ds_bpermute_b32 v10, v11, v9
	v_lshlrev_b32_e32 v11, 2, v33
	v_xor_b32_e32 v11, 16, v11
	s_waitcnt lgkmcnt(0)
	v_add_f32_e32 v9, v9, v10
	ds_bpermute_b32 v10, v11, v9
	v_lshlrev_b32_e32 v11, 2, v34
	v_xor_b32_e32 v11, 32, v11
	s_waitcnt lgkmcnt(0)
	v_add_f32_e32 v9, v9, v10
	ds_bpermute_b32 v10, v11, v9
	s_waitcnt lgkmcnt(0)
	v_add_f32_e32 v9, v9, v10
	v_fmamk_f32 v9, v9, 0x3c000000, v207
	v_mul_f32_e32 v10, 0x4f800000, v9
	v_cmp_gt_f32_e32 vcc, s87, v9
	s_waitcnt vmcnt(0)
	v_lshlrev_b32_e32 v12, 16, v16
	v_cndmask_b32_e32 v9, v9, v10, vcc
	v_sqrt_f32_e32 v10, v9
	v_and_b32_e32 v13, 0xffff0000, v16
	v_lshlrev_b32_e32 v22, 16, v15
	v_and_b32_e32 v23, 0xffff0000, v15
	v_add_u32_e32 v11, -1, v10
	v_fma_f32 v16, -v11, v10, v9
	v_cmp_ge_f32_e64 s[0:1], 0, v16
	v_add_u32_e32 v16, 1, v10
	s_nop 0
	v_cndmask_b32_e64 v11, v10, v11, s[0:1]
	v_fma_f32 v10, -v16, v10, v9
	v_cmp_lt_f32_e64 s[0:1], 0, v10
	s_nop 1
	v_cndmask_b32_e64 v10, v11, v16, s[0:1]
	v_mul_f32_e32 v11, 0x37800000, v10
	v_cndmask_b32_e32 v10, v10, v11, vcc
	v_cmp_class_f32_e32 vcc, v9, v208
	v_and_b32_e32 v11, 0xffff0000, v14
	s_nop 0
	v_cndmask_b32_e32 v9, v10, v9, vcc
	v_div_scale_f32 v16, s[0:1], v9, v9, s88
	v_rcp_f32_e32 v28, v16
	v_lshlrev_b32_e32 v10, 16, v14
	v_fma_f32 v14, -v16, v28, 1.0
	v_fmac_f32_e32 v28, v14, v28
	v_div_scale_f32 v14, vcc, s88, v9, s88
	v_mul_f32_e32 v15, v14, v28
	v_fma_f32 v29, -v16, v15, v14
	v_fmac_f32_e32 v15, v29, v28
	v_fma_f32 v14, -v16, v15, v14
	v_div_fmas_f32 v14, v14, v28, v15
	v_div_fixup_f32 v14, v14, v9, s88
	v_pk_mul_f32 v[28:29], v[14:15], v[30:31] op_sel_hi:[0,1]
	v_pk_mul_f32 v[26:27], v[14:15], v[26:27] op_sel_hi:[0,1]
	v_pk_mul_f32 v[28:29], v[4:5], v[28:29]
	v_pk_mul_f32 v[26:27], v[6:7], v[26:27]
	v_pk_mul_f32 v[10:11], v[28:29], v[10:11]
	v_pk_mul_f32 v[22:23], v[26:27], v[22:23]
	v_cvt_pk_bf16_f32 v10, v10, v11
	v_cvt_pk_bf16_f32 v11, v22, v23
	v_pk_mul_f32 v[22:23], v[14:15], v[24:25] op_sel_hi:[0,1]
	v_pk_mul_f32 v[14:15], v[14:15], v[20:21] op_sel_hi:[0,1]
	v_pk_mul_f32 v[22:23], v[0:1], v[22:23]
	v_pk_mul_f32 v[14:15], v[2:3], v[14:15]
	v_lshlrev_b32_e32 v16, 16, v17
	v_and_b32_e32 v17, 0xffff0000, v17
	v_pk_mul_f32 v[12:13], v[22:23], v[12:13]
	v_pk_mul_f32 v[14:15], v[14:15], v[16:17]
	v_cvt_pk_bf16_f32 v12, v12, v13
	v_cvt_pk_bf16_f32 v13, v14, v15
	v_lshl_add_u64 v[14:15], s[8:9], 0, v[18:19]
	v_add_u32_e32 v9, 0x140, v8
	global_store_dwordx4 v[14:15], v[10:13], off
	v_ashrrev_i32_e32 v14, 4, v9
	v_ashrrev_i32_e32 v15, 31, v14
	v_lshl_add_u64 v[14:15], s[4:5], 0, v[14:15]
	v_lshlrev_b64 v[14:15], 9, v[14:15]
	v_lshl_add_u64 v[14:15], v[14:15], 0, v[200:201]
	v_lshlrev_b64 v[18:19], 1, v[14:15]
	v_lshl_add_u32 v10, v9, 4, s43
	v_lshl_add_u64 v[14:15], s[52:53], 0, v[18:19]
	ds_read_b128 v[10:13], v10
	v_mbcnt_lo_u32_b32 v9, -1, 0
	v_mbcnt_hi_u32_b32 v9, -1, v9
	v_mbcnt_lo_u32_b32 v32, -1, 0
	v_mbcnt_hi_u32_b32 v32, -1, v32
	v_mbcnt_lo_u32_b32 v33, -1, 0
	v_mbcnt_hi_u32_b32 v33, -1, v33
	v_mbcnt_lo_u32_b32 v34, -1, 0
	v_mbcnt_hi_u32_b32 v34, -1, v34
	global_load_dwordx4 v[14:17], v[14:15], off
	s_waitcnt lgkmcnt(0)
	v_lshlrev_b32_e32 v30, 16, v10
	v_and_b32_e32 v31, 0xffff0000, v10
	v_lshlrev_b32_e32 v26, 16, v11
	v_and_b32_e32 v27, 0xffff0000, v11
	v_pk_mul_f32 v[10:11], v[30:31], v[30:31]
	v_pk_mul_f32 v[28:29], v[26:27], v[26:27]
	v_add_f32_e32 v10, v10, v11
	v_lshlrev_b32_e32 v24, 16, v12
	v_and_b32_e32 v25, 0xffff0000, v12
	v_add_f32_e32 v10, v10, v28
	v_lshlrev_b32_e32 v20, 16, v13
	v_and_b32_e32 v21, 0xffff0000, v13
	v_pk_mul_f32 v[12:13], v[24:25], v[24:25]
	v_add_f32_e32 v10, v10, v29
	v_add_f32_e32 v10, v10, v12
	v_pk_mul_f32 v[22:23], v[20:21], v[20:21]
	v_add_f32_e32 v10, v10, v13
	v_lshlrev_b32_e32 v9, 2, v9
	v_add_f32_e32 v10, v10, v22
	v_xor_b32_e32 v9, 4, v9
	v_add_f32_e32 v10, v10, v23
	ds_bpermute_b32 v9, v9, v10
	v_lshlrev_b32_e32 v11, 2, v32
	v_xor_b32_e32 v11, 8, v11
	s_waitcnt lgkmcnt(0)
	v_add_f32_e32 v9, v10, v9
	ds_bpermute_b32 v10, v11, v9
	v_lshlrev_b32_e32 v11, 2, v33
	v_xor_b32_e32 v11, 16, v11
	s_waitcnt lgkmcnt(0)
	v_add_f32_e32 v9, v9, v10
	ds_bpermute_b32 v10, v11, v9
	v_lshlrev_b32_e32 v11, 2, v34
	v_xor_b32_e32 v11, 32, v11
	s_waitcnt lgkmcnt(0)
	v_add_f32_e32 v9, v9, v10
	ds_bpermute_b32 v10, v11, v9
	s_waitcnt lgkmcnt(0)
	v_add_f32_e32 v9, v9, v10
	v_fmamk_f32 v9, v9, 0x3c000000, v207
	v_mul_f32_e32 v10, 0x4f800000, v9
	v_cmp_gt_f32_e32 vcc, s87, v9
	s_waitcnt vmcnt(0)
; __device__ __forceinline__ float shflx(float v, int mask) { return __builtin_bit_cast(float, __builtin_amdgcn_ds_bpermute((lane_id_v() ^ mask) << 2, __builtin_bit_cast(int, v))); }
; __device__ __forceinline__ unsigned cvtpk(float lo, float hi) { f32x2_t v = {lo, hi}; bf16x2_t b = __builtin_convertvector(v, bf16x2_t); return __builtin_bit_cast(unsigned, b); }
; __global__ void __launch_bounds__(512, 2) fwd_mega(Args a) {
;     ...
;                 for (int j = 0; j < 8; ++j) { const int id = j * 64 + lane, row = id >> 4;
;                     const u32x4 t = *(const u32x4*)(T + id * 16);
;                     float e[8] = {bflo(t.x), bfhi(t.x), bflo(t.y), bfhi(t.y), bflo(t.z), bfhi(t.z), bflo(t.w), bfhi(t.w)};
;                     float ss = 0.f;
; #pragma unroll
;                     for (int k = 0; k < 8; ++k) ss += e[k] * e[k];
;                     ss += shflx(ss, 1); ss += shflx(ss, 2); ss += shflx(ss, 4); ss += shflx(ss, 8);
;                     const float rs = 0.8f / sqrtf(ss * (1.f / 128.f) + 1e-5f);
;                     const size_t go = (qrow0 + wave * 32 + row) * 512 + h * 128 + c16 * 8; const u32x4 g = *(const u32x4*)(GD + go);
;                     u32x4 w; w.x = cvtpk(e[0] * rs * sw0[0] * bflo(g.x), e[1] * rs * sw0[1] * bfhi(g.x)); w.y = cvtpk(e[2] * rs * sw0[2] * bflo(g.y), e[3] * rs * sw0[3] * bfhi(g.y));
;                     w.z = cvtpk(e[4] * rs * sw1[0] * bflo(g.z), e[5] * rs * sw1[1] * bfhi(g.z)); w.w = cvtpk(e[6] * rs * sw1[2] * bflo(g.w), e[7] * rs * sw1[3] * bfhi(g.w));
;                     *(u32x4*)(XD + go) = w; }
	v_lshlrev_b32_e32 v12, 16, v16
	v_cndmask_b32_e32 v9, v9, v10, vcc
	v_sqrt_f32_e32 v10, v9
	v_and_b32_e32 v13, 0xffff0000, v16
	v_lshlrev_b32_e32 v22, 16, v15
	v_and_b32_e32 v23, 0xffff0000, v15
	v_add_u32_e32 v11, -1, v10
	v_fma_f32 v16, -v11, v10, v9
	v_cmp_ge_f32_e64 s[0:1], 0, v16
	v_add_u32_e32 v16, 1, v10
	s_nop 0
	v_cndmask_b32_e64 v11, v10, v11, s[0:1]
	v_fma_f32 v10, -v16, v10, v9
	v_cmp_lt_f32_e64 s[0:1], 0, v10
	s_nop 1
	v_cndmask_b32_e64 v10, v11, v16, s[0:1]
	v_mul_f32_e32 v11, 0x37800000, v10
	v_cndmask_b32_e32 v10, v10, v11, vcc
	v_cmp_class_f32_e32 vcc, v9, v208
	v_and_b32_e32 v11, 0xffff0000, v14
	s_nop 0
	v_cndmask_b32_e32 v9, v10, v9, vcc
	v_div_scale_f32 v16, s[0:1], v9, v9, s88
	v_rcp_f32_e32 v28, v16
	v_lshlrev_b32_e32 v10, 16, v14
	v_fma_f32 v14, -v16, v28, 1.0
	v_fmac_f32_e32 v28, v14, v28
	v_div_scale_f32 v14, vcc, s88, v9, s88
	v_mul_f32_e32 v15, v14, v28
	v_fma_f32 v29, -v16, v15, v14
	v_fmac_f32_e32 v15, v29, v28
	v_fma_f32 v14, -v16, v15, v14
	v_div_fmas_f32 v14, v14, v28, v15
	v_div_fixup_f32 v14, v14, v9, s88
	v_pk_mul_f32 v[28:29], v[14:15], v[30:31] op_sel_hi:[0,1]
	v_pk_mul_f32 v[26:27], v[14:15], v[26:27] op_sel_hi:[0,1]
	v_pk_mul_f32 v[28:29], v[4:5], v[28:29]
	v_pk_mul_f32 v[26:27], v[6:7], v[26:27]
	v_pk_mul_f32 v[10:11], v[28:29], v[10:11]
	v_pk_mul_f32 v[22:23], v[26:27], v[22:23]
	v_cvt_pk_bf16_f32 v10, v10, v11
	v_cvt_pk_bf16_f32 v11, v22, v23
	v_pk_mul_f32 v[22:23], v[14:15], v[24:25] op_sel_hi:[0,1]
	v_pk_mul_f32 v[14:15], v[14:15], v[20:21] op_sel_hi:[0,1]
	v_pk_mul_f32 v[22:23], v[0:1], v[22:23]
	v_pk_mul_f32 v[14:15], v[2:3], v[14:15]
	v_lshlrev_b32_e32 v16, 16, v17
	v_and_b32_e32 v17, 0xffff0000, v17
	v_pk_mul_f32 v[12:13], v[22:23], v[12:13]
	v_pk_mul_f32 v[14:15], v[14:15], v[16:17]
	v_cvt_pk_bf16_f32 v12, v12, v13
	v_cvt_pk_bf16_f32 v13, v14, v15
	v_lshl_add_u64 v[14:15], s[8:9], 0, v[18:19]
	v_add_u32_e32 v9, 0x180, v8
	global_store_dwordx4 v[14:15], v[10:13], off
	v_ashrrev_i32_e32 v14, 4, v9
	v_ashrrev_i32_e32 v15, 31, v14
	v_lshl_add_u64 v[14:15], s[4:5], 0, v[14:15]
	v_lshlrev_b64 v[14:15], 9, v[14:15]
	v_lshl_add_u64 v[14:15], v[14:15], 0, v[200:201]
	v_lshlrev_b64 v[18:19], 1, v[14:15]
	v_lshl_add_u32 v10, v9, 4, s43
	v_lshl_add_u64 v[14:15], s[52:53], 0, v[18:19]
	ds_read_b128 v[10:13], v10
	v_mbcnt_lo_u32_b32 v9, -1, 0
	v_mbcnt_hi_u32_b32 v9, -1, v9
	v_mbcnt_lo_u32_b32 v32, -1, 0
	v_mbcnt_hi_u32_b32 v32, -1, v32
	v_mbcnt_lo_u32_b32 v33, -1, 0
	v_mbcnt_hi_u32_b32 v33, -1, v33
	v_mbcnt_lo_u32_b32 v34, -1, 0
	v_mbcnt_hi_u32_b32 v34, -1, v34
	global_load_dwordx4 v[14:17], v[14:15], off
	s_waitcnt lgkmcnt(0)
	v_lshlrev_b32_e32 v30, 16, v10
	v_and_b32_e32 v31, 0xffff0000, v10
	v_lshlrev_b32_e32 v26, 16, v11
	v_and_b32_e32 v27, 0xffff0000, v11
	v_pk_mul_f32 v[10:11], v[30:31], v[30:31]
	v_pk_mul_f32 v[28:29], v[26:27], v[26:27]
	v_add_f32_e32 v10, v10, v11
	v_lshlrev_b32_e32 v24, 16, v12
	v_and_b32_e32 v25, 0xffff0000, v12
	v_add_f32_e32 v10, v10, v28
	v_lshlrev_b32_e32 v20, 16, v13
	v_and_b32_e32 v21, 0xffff0000, v13
	v_pk_mul_f32 v[12:13], v[24:25], v[24:25]
	v_add_f32_e32 v10, v10, v29
	v_add_f32_e32 v10, v10, v12
	v_pk_mul_f32 v[22:23], v[20:21], v[20:21]
	v_add_f32_e32 v10, v10, v13
	v_lshlrev_b32_e32 v9, 2, v9
	v_add_f32_e32 v10, v10, v22
	v_xor_b32_e32 v9, 4, v9
	v_add_f32_e32 v10, v10, v23
	ds_bpermute_b32 v9, v9, v10
	v_lshlrev_b32_e32 v11, 2, v32
	v_xor_b32_e32 v11, 8, v11
	s_waitcnt lgkmcnt(0)
	v_add_f32_e32 v9, v10, v9
	ds_bpermute_b32 v10, v11, v9
	v_lshlrev_b32_e32 v11, 2, v33
	v_xor_b32_e32 v11, 16, v11
	s_waitcnt lgkmcnt(0)
	v_add_f32_e32 v9, v9, v10
	ds_bpermute_b32 v10, v11, v9
	v_lshlrev_b32_e32 v11, 2, v34
	v_xor_b32_e32 v11, 32, v11
	s_waitcnt lgkmcnt(0)
	v_add_f32_e32 v9, v9, v10
	ds_bpermute_b32 v10, v11, v9
	s_waitcnt lgkmcnt(0)
	v_add_f32_e32 v9, v9, v10
	v_fmamk_f32 v9, v9, 0x3c000000, v207
	v_mul_f32_e32 v10, 0x4f800000, v9
	v_cmp_gt_f32_e32 vcc, s87, v9
	s_waitcnt vmcnt(0)
; __device__ __forceinline__ float shflx(float v, int mask) { return __builtin_bit_cast(float, __builtin_amdgcn_ds_bpermute((lane_id_v() ^ mask) << 2, __builtin_bit_cast(int, v))); }
; __device__ __forceinline__ unsigned cvtpk(float lo, float hi) { f32x2_t v = {lo, hi}; bf16x2_t b = __builtin_convertvector(v, bf16x2_t); return __builtin_bit_cast(unsigned, b); }
; __global__ void __launch_bounds__(512, 2) fwd_mega(Args a) {
;     ...
;                 for (int j = 0; j < 8; ++j) { const int id = j * 64 + lane, row = id >> 4;
;                     const u32x4 t = *(const u32x4*)(T + id * 16);
;                     float e[8] = {bflo(t.x), bfhi(t.x), bflo(t.y), bfhi(t.y), bflo(t.z), bfhi(t.z), bflo(t.w), bfhi(t.w)};
;                     float ss = 0.f;
; #pragma unroll
;                     for (int k = 0; k < 8; ++k) ss += e[k] * e[k];
;                     ss += shflx(ss, 1); ss += shflx(ss, 2); ss += shflx(ss, 4); ss += shflx(ss, 8);
;                     const float rs = 0.8f / sqrtf(ss * (1.f / 128.f) + 1e-5f);
;                     const size_t go = (qrow0 + wave * 32 + row) * 512 + h * 128 + c16 * 8; const u32x4 g = *(const u32x4*)(GD + go);
;                     u32x4 w; w.x = cvtpk(e[0] * rs * sw0[0] * bflo(g.x), e[1] * rs * sw0[1] * bfhi(g.x)); w.y = cvtpk(e[2] * rs * sw0[2] * bflo(g.y), e[3] * rs * sw0[3] * bfhi(g.y));
;                     w.z = cvtpk(e[4] * rs * sw1[0] * bflo(g.z), e[5] * rs * sw1[1] * bfhi(g.z)); w.w = cvtpk(e[6] * rs * sw1[2] * bflo(g.w), e[7] * rs * sw1[3] * bfhi(g.w));
;                     *(u32x4*)(XD + go) = w; }
	v_lshlrev_b32_e32 v12, 16, v16
	v_cndmask_b32_e32 v9, v9, v10, vcc
	v_sqrt_f32_e32 v10, v9
	v_and_b32_e32 v13, 0xffff0000, v16
	v_lshlrev_b32_e32 v22, 16, v15
	v_and_b32_e32 v23, 0xffff0000, v15
	v_add_u32_e32 v11, -1, v10
	v_fma_f32 v16, -v11, v10, v9
	v_cmp_ge_f32_e64 s[0:1], 0, v16
	v_add_u32_e32 v16, 1, v10
	s_nop 0
	v_cndmask_b32_e64 v11, v10, v11, s[0:1]
	v_fma_f32 v10, -v16, v10, v9
	v_cmp_lt_f32_e64 s[0:1], 0, v10
	s_nop 1
	v_cndmask_b32_e64 v10, v11, v16, s[0:1]
	v_mul_f32_e32 v11, 0x37800000, v10
	v_cndmask_b32_e32 v10, v10, v11, vcc
	v_cmp_class_f32_e32 vcc, v9, v208
	v_and_b32_e32 v11, 0xffff0000, v14
	s_nop 0
	v_cndmask_b32_e32 v9, v10, v9, vcc
	v_div_scale_f32 v16, s[0:1], v9, v9, s88
	v_rcp_f32_e32 v28, v16
	v_lshlrev_b32_e32 v10, 16, v14
	v_fma_f32 v14, -v16, v28, 1.0
	v_fmac_f32_e32 v28, v14, v28
	v_div_scale_f32 v14, vcc, s88, v9, s88
	v_mul_f32_e32 v15, v14, v28
	v_fma_f32 v29, -v16, v15, v14
	v_fmac_f32_e32 v15, v29, v28
	v_fma_f32 v14, -v16, v15, v14
	v_div_fmas_f32 v14, v14, v28, v15
	v_div_fixup_f32 v14, v14, v9, s88
	v_pk_mul_f32 v[28:29], v[14:15], v[30:31] op_sel_hi:[0,1]
	v_pk_mul_f32 v[26:27], v[14:15], v[26:27] op_sel_hi:[0,1]
	v_pk_mul_f32 v[28:29], v[4:5], v[28:29]
	v_pk_mul_f32 v[26:27], v[6:7], v[26:27]
	v_pk_mul_f32 v[10:11], v[28:29], v[10:11]
	v_pk_mul_f32 v[22:23], v[26:27], v[22:23]
	v_cvt_pk_bf16_f32 v10, v10, v11
	v_cvt_pk_bf16_f32 v11, v22, v23
	v_pk_mul_f32 v[22:23], v[14:15], v[24:25] op_sel_hi:[0,1]
	v_pk_mul_f32 v[14:15], v[14:15], v[20:21] op_sel_hi:[0,1]
	v_pk_mul_f32 v[22:23], v[0:1], v[22:23]
	v_pk_mul_f32 v[14:15], v[2:3], v[14:15]
	v_lshlrev_b32_e32 v16, 16, v17
	v_and_b32_e32 v17, 0xffff0000, v17
	v_pk_mul_f32 v[12:13], v[22:23], v[12:13]
	v_pk_mul_f32 v[14:15], v[14:15], v[16:17]
	v_cvt_pk_bf16_f32 v12, v12, v13
	v_cvt_pk_bf16_f32 v13, v14, v15
	v_lshl_add_u64 v[14:15], s[8:9], 0, v[18:19]
	global_store_dwordx4 v[14:15], v[10:13], off
	s_nop 1
	v_add_u32_e32 v12, 0x1c0, v8
	v_lshl_add_u32 v8, v12, 4, s43
	v_ashrrev_i32_e32 v12, 4, v12
	v_ashrrev_i32_e32 v13, 31, v12
	v_lshl_add_u64 v[12:13], s[4:5], 0, v[12:13]
	v_lshlrev_b64 v[12:13], 9, v[12:13]
	v_lshl_add_u64 v[12:13], v[12:13], 0, v[200:201]
	v_lshlrev_b64 v[16:17], 1, v[12:13]
	v_lshl_add_u64 v[12:13], s[52:53], 0, v[16:17]
	ds_read_b128 v[8:11], v8
	v_mbcnt_lo_u32_b32 v18, -1, 0
	v_mbcnt_hi_u32_b32 v18, -1, v18
	v_mbcnt_lo_u32_b32 v30, -1, 0
	v_mbcnt_hi_u32_b32 v30, -1, v30
	v_mbcnt_lo_u32_b32 v31, -1, 0
	v_mbcnt_hi_u32_b32 v31, -1, v31
	v_mbcnt_lo_u32_b32 v32, -1, 0
	v_mbcnt_hi_u32_b32 v32, -1, v32
	global_load_dwordx4 v[12:15], v[12:13], off
	s_waitcnt lgkmcnt(0)
	v_lshlrev_b32_e32 v28, 16, v8
	v_and_b32_e32 v29, 0xffff0000, v8
	v_lshlrev_b32_e32 v24, 16, v9
	v_and_b32_e32 v25, 0xffff0000, v9
	v_pk_mul_f32 v[8:9], v[28:29], v[28:29]
	v_pk_mul_f32 v[26:27], v[24:25], v[24:25]
	v_add_f32_e32 v8, v8, v9
	v_lshlrev_b32_e32 v18, 2, v18
	v_lshlrev_b32_e32 v22, 16, v10
	v_and_b32_e32 v23, 0xffff0000, v10
	v_add_f32_e32 v8, v8, v26
	v_xor_b32_e32 v33, 4, v18
	v_lshlrev_b32_e32 v18, 16, v11
	v_and_b32_e32 v19, 0xffff0000, v11
	v_pk_mul_f32 v[10:11], v[22:23], v[22:23]
	v_add_f32_e32 v8, v8, v27
	v_add_f32_e32 v8, v8, v10
	v_pk_mul_f32 v[20:21], v[18:19], v[18:19]
	v_add_f32_e32 v8, v8, v11
	v_add_f32_e32 v8, v8, v20
	v_add_f32_e32 v8, v8, v21
	ds_bpermute_b32 v9, v33, v8
	v_lshlrev_b32_e32 v10, 2, v30
	v_xor_b32_e32 v10, 8, v10
	s_waitcnt lgkmcnt(0)
	v_add_f32_e32 v8, v8, v9
	ds_bpermute_b32 v9, v10, v8
	v_lshlrev_b32_e32 v10, 2, v31
	v_xor_b32_e32 v10, 16, v10
	s_waitcnt lgkmcnt(0)
	v_add_f32_e32 v8, v8, v9
	ds_bpermute_b32 v9, v10, v8
	v_lshlrev_b32_e32 v10, 2, v32
	v_xor_b32_e32 v10, 32, v10
	s_waitcnt lgkmcnt(0)
	v_add_f32_e32 v8, v8, v9
	ds_bpermute_b32 v9, v10, v8
	s_waitcnt lgkmcnt(0)
	v_add_f32_e32 v8, v8, v9
	v_fmamk_f32 v8, v8, 0x3c000000, v207
	v_mul_f32_e32 v9, 0x4f800000, v8
	v_cmp_gt_f32_e32 vcc, s87, v8
	s_waitcnt vmcnt(0)
	v_lshlrev_b32_e32 v10, 16, v13
	v_cndmask_b32_e32 v11, v8, v9, vcc
	v_sqrt_f32_e32 v20, v11
	v_lshlrev_b32_e32 v8, 16, v14
	v_and_b32_e32 v9, 0xffff0000, v14
	v_add_u32_e32 v14, -1, v20
	v_fma_f32 v21, -v14, v20, v11
	v_cmp_ge_f32_e64 s[0:1], 0, v21
	v_add_u32_e32 v21, 1, v20
	s_nop 0
	v_cndmask_b32_e64 v14, v20, v14, s[0:1]
	v_fma_f32 v20, -v21, v20, v11
	v_cmp_lt_f32_e64 s[0:1], 0, v20
	s_nop 1
	v_cndmask_b32_e64 v14, v14, v21, s[0:1]
	v_mul_f32_e32 v20, 0x37800000, v14
	v_cndmask_b32_e32 v14, v14, v20, vcc
	v_cmp_class_f32_e32 vcc, v11, v208
	v_lshlrev_b32_e32 v20, 16, v12
	v_and_b32_e32 v21, 0xffff0000, v12
	v_cndmask_b32_e32 v14, v14, v11, vcc
	v_div_scale_f32 v26, s[0:1], v14, v14, s88
	v_rcp_f32_e32 v27, v26
	v_and_b32_e32 v11, 0xffff0000, v13
	s_mov_b64 s[0:1], 0
	v_fma_f32 v12, -v26, v27, 1.0
	v_fmac_f32_e32 v27, v12, v27
	v_div_scale_f32 v12, vcc, s88, v14, s88
	v_mul_f32_e32 v13, v12, v27
	v_fma_f32 v30, -v26, v13, v12
	v_fmac_f32_e32 v13, v30, v27
	v_fma_f32 v12, -v26, v13, v12
	v_div_fmas_f32 v12, v12, v27, v13
	v_div_fixup_f32 v12, v12, v14, s88
	v_pk_mul_f32 v[26:27], v[12:13], v[28:29] op_sel_hi:[0,1]
	v_pk_mul_f32 v[4:5], v[4:5], v[26:27]
	s_nop 0
	v_pk_mul_f32 v[4:5], v[4:5], v[20:21]
	v_pk_mul_f32 v[20:21], v[12:13], v[24:25] op_sel_hi:[0,1]
	v_pk_mul_f32 v[6:7], v[6:7], v[20:21]
	v_cvt_pk_bf16_f32 v4, v4, v5
	v_pk_mul_f32 v[6:7], v[6:7], v[10:11]
	s_nop 0
	v_cvt_pk_bf16_f32 v5, v6, v7
	v_pk_mul_f32 v[6:7], v[12:13], v[22:23] op_sel_hi:[0,1]
	v_pk_mul_f32 v[0:1], v[0:1], v[6:7]
	s_nop 0
	v_pk_mul_f32 v[0:1], v[0:1], v[8:9]
	s_nop 0
	v_cvt_pk_bf16_f32 v6, v0, v1
	v_pk_mul_f32 v[0:1], v[12:13], v[18:19] op_sel_hi:[0,1]
	v_pk_mul_f32 v[0:1], v[2:3], v[0:1]
	v_lshlrev_b32_e32 v2, 16, v15
	v_and_b32_e32 v3, 0xffff0000, v15
	v_pk_mul_f32 v[0:1], v[0:1], v[2:3]
	s_nop 0
	v_cvt_pk_bf16_f32 v7, v0, v1
	v_lshl_add_u64 v[0:1], s[8:9], 0, v[16:17]
	global_store_dwordx4 v[0:1], v[4:7], off

.LBB0_1226:
	v_add_f32_e32 v157, v48, v49
	s_add_u32 s10, s58, 0x78000
	v_add_co_u32_e32 v48, vcc, 0x50000, v148
	s_addc_u32 s11, s59, 0
	s_nop 0
	v_addc_co_u32_e32 v49, vcc, 0, v149, vcc
	global_load_dwordx4 v[116:119], v[48:49], off
	global_load_dwordx4 v[124:127], v146, s[10:11]
	global_load_dwordx4 v[120:123], v200, s[10:11]
	v_add_f32_e32 v50, v159, v160
	v_add_f32_e32 v50, 0, v50
	v_fmac_f32_e32 v157, v50, v161
	v_mul_f32_e32 v157, 0.5, v157
	s_mov_b32 s51, 5
	s_mov_b32 s60, 0xa000
	s_waitcnt lgkmcnt(0)
	s_barrier
	s_branch .LBB0_1228
.LBB0_1227:
	s_min_u32 s10, s61, 0x7e
	s_lshl_b32 s10, s10, 6
	s_add_i32 s16, s10, 0x140
	s_mul_i32 s10, s16, 0x600
	s_add_u32 s10, s58, s10
	s_addc_u32 s11, s59, 0
	s_lshl_b32 s16, s16, 10
	v_fma_f32 v50, v157, v158, v159
	v_fma_f32 v157, v50, v161, v48
	v_lshl_add_u64 v[48:49], v[148:149], 0, s[16:17]
	global_load_dwordx4 v[116:119], v[48:49], off
	global_load_dwordx4 v[124:127], v146, s[10:11]
	global_load_dwordx4 v[120:123], v200, s[10:11]
	s_add_i32 s51, s51, 2
	s_addk_i32 s60, 0x4000
	s_cmpk_gt_u32 s61, 0x81
	s_waitcnt lgkmcnt(0)
	s_barrier
	s_cbranch_scc1 .LBB0_1246

; #define SBAR() __builtin_amdgcn_sched_barrier(0)
; #define PK4(P, BASE, OUT) do { u32x4 w = {cvtpk_a(P[BASE + 0], P[BASE + 1]), cvtpk_a(P[BASE + 2], P[BASE + 3]), cvtpk_a(P[BASE + 4], P[BASE + 5]), cvtpk_a(P[BASE + 6], P[BASE + 7])}; \
;     OUT = *reinterpret_cast<bf16x8*>(&w); } while (0)
; #define SWAIT() asm volatile("s_waitcnt vmcnt(3)" ::: "memory")
; __device__ __forceinline__ float exp_pack(f32x16& p0, f32x16& p1, bf16x8& pa0, bf16x8& pa1, bf16x8& pa2, bf16x8& pa3) {
; #pragma unroll
;     for (int r = 0; r < 16; ++r) p0[r] = __builtin_amdgcn_exp2f(p0[r]);
; #pragma unroll
;     for (int r = 0; r < 16; ++r) p1[r] = __builtin_amdgcn_exp2f(p1[r]);
;     SBAR(); asm volatile("s_nop 1" ::: "memory"); SBAR();
;     ...
;     PK4(p0, 0, pa0); PK4(p0, 8, pa1); PK4(p1, 0, pa2); PK4(p1, 8, pa3);
;     ...
;     float ps0 = p0[0], ps1 = p1[0];
; #pragma unroll
;     for (int r = 1; r < 16; ++r) { ps0 += p0[r]; ps1 += p1[r]; }
;     float ps = ps0 + ps1;
;     { auto rr = __builtin_amdgcn_permlane32_swap(__float_as_uint(ps), __float_as_uint(ps), false, false);
;       ps = __uint_as_float(rr[0]) + __uint_as_float(rr[1]); }
;     return ps;
; template <bool MLA>
; __device__ __forceinline__ void attn_core(const bf16_t* __restrict__ Qb, const bf16_t* __restrict__ Kh, const bf16_t* __restrict__ Vh, int seq, char* lds,
;                                           f32x16 (&o)[Cfg<MLA>::NCB], const int wid  , const int g  ) {
;     ...
;         SWAIT(); if (j + 2 < NT) SWRITE(((j + 2) % 3) * SHM_K, ((j + 2) & 3) * SHM_V, SE);
.LBB0_1233:
	v_exp_f32_e32 v64, v64
	v_exp_f32_e32 v65, v65
	v_exp_f32_e32 v66, v66
	v_exp_f32_e32 v67, v67
	v_exp_f32_e32 v68, v68
	v_exp_f32_e32 v69, v69
	v_exp_f32_e32 v70, v70
	v_exp_f32_e32 v71, v71
	v_exp_f32_e32 v72, v72
	v_exp_f32_e32 v73, v73
	v_exp_f32_e32 v74, v74
	v_exp_f32_e32 v75, v75
	v_exp_f32_e32 v76, v76
	v_exp_f32_e32 v77, v77
	v_exp_f32_e32 v78, v78
	v_exp_f32_e32 v79, v79
	v_exp_f32_e32 v48, v48
	v_exp_f32_e32 v49, v49
	v_exp_f32_e32 v50, v50
	v_exp_f32_e32 v51, v51
	v_exp_f32_e32 v52, v52
	v_exp_f32_e32 v53, v53
	v_exp_f32_e32 v54, v54
	v_exp_f32_e32 v55, v55
	v_exp_f32_e32 v56, v56
	v_exp_f32_e32 v57, v57
	v_exp_f32_e32 v58, v58
	v_exp_f32_e32 v59, v59
	v_exp_f32_e32 v60, v60
	v_exp_f32_e32 v61, v61
	v_exp_f32_e32 v62, v62
	v_exp_f32_e32 v63, v63
	s_nop 1
	v_cvt_pk_bf16_f32 v140, v64, v65
	v_cvt_pk_bf16_f32 v141, v66, v67
	v_cvt_pk_bf16_f32 v142, v68, v69
	v_cvt_pk_bf16_f32 v143, v70, v71
	v_cvt_pk_bf16_f32 v136, v72, v73
	v_cvt_pk_bf16_f32 v137, v74, v75
	v_cvt_pk_bf16_f32 v138, v76, v77
	v_cvt_pk_bf16_f32 v139, v78, v79
	v_cvt_pk_bf16_f32 v132, v48, v49
	v_add_f32_e32 v64, v64, v65
	v_add_f32_e32 v48, v48, v49
	v_add_f32_e32 v49, v66, v64
	v_add_f32_e32 v48, v50, v48
	v_add_f32_e32 v49, v67, v49
	v_add_f32_e32 v48, v51, v48
	v_add_f32_e32 v49, v68, v49
	v_add_f32_e32 v48, v52, v48
	v_add_f32_e32 v49, v69, v49
	v_add_f32_e32 v48, v53, v48
	v_add_f32_e32 v49, v70, v49
	v_add_f32_e32 v48, v54, v48
	v_add_f32_e32 v49, v71, v49
	v_add_f32_e32 v48, v55, v48
	v_add_f32_e32 v49, v72, v49
	v_add_f32_e32 v48, v56, v48
	v_add_f32_e32 v49, v73, v49
	v_add_f32_e32 v48, v57, v48
	v_add_f32_e32 v49, v74, v49
	v_add_f32_e32 v48, v58, v48
	v_add_f32_e32 v49, v75, v49
	v_add_f32_e32 v48, v59, v48
	v_add_f32_e32 v49, v76, v49
	v_add_f32_e32 v48, v60, v48
	v_add_f32_e32 v49, v77, v49
	v_add_f32_e32 v48, v61, v48
	v_add_f32_e32 v49, v78, v49
	v_add_f32_e32 v48, v62, v48
	v_add_f32_e32 v49, v79, v49
	v_add_f32_e32 v48, v63, v48
	v_cvt_pk_bf16_f32 v133, v50, v51
	v_cvt_pk_bf16_f32 v134, v52, v53
	v_cvt_pk_bf16_f32 v135, v54, v55
	v_cvt_pk_bf16_f32 v128, v56, v57
	v_cvt_pk_bf16_f32 v129, v58, v59
	v_cvt_pk_bf16_f32 v130, v60, v61
	v_cvt_pk_bf16_f32 v131, v62, v63
	v_add_f32_e32 v159, v48, v49
	s_waitcnt vmcnt(3)
	s_cmpk_gt_u32 s61, 0x81
	s_cbranch_scc1 .LBB0_1236
	s_add_i32 s10, s60, 0xffffe000
	s_and_b32 s10, s10, 0x4000
	v_add_u32_e32 v48, s10, v145
	s_add_i32 s10, s51, 0xffff
	s_mul_i32 s11, s10, 0xab
	s_bfe_u32 s11, s11, 0x70009
	s_mul_i32 s11, s11, 3
	s_sub_i32 s10, s10, s11
	s_and_b32 s10, s10, 0xff
	s_mulk_i32 s10, 0x4400
	s_add_i32 s16, s10, 0
	s_waitcnt vmcnt(5)
	ds_write_b128 v48, v[112:115]
	v_add_u32_e32 v48, s16, v144
	s_and_b64 vcc, exec, s[4:5]
	s_waitcnt vmcnt(4)
	ds_write_b128 v48, v[108:111] offset:32768
	s_cbranch_vccnz .LBB0_1236
	v_add_u32_e32 v48, s16, v150
	s_waitcnt vmcnt(3)
	ds_write_b128 v48, v[104:107] offset:32768
; __device__ __forceinline__ float max3f(float a, float b, float c) { return __builtin_fmaxf(__builtin_fmaxf(a, b), c); }
; __device__ __forceinline__ void rowmax_adjust(f32x16& p0, f32x16& p1, float& m2, f32x16& negm, float& alpha, const bool first) {
;     constexpr float THR2 = THR * 1.4426950408889634f;
;     float pmax = max3f(p0[0], p0[1], p0[2]);
; #pragma unroll
;     for (int r = 3; r < 15; r += 2) pmax = max3f(pmax, p0[r], p0[r + 1]);
;     pmax = max3f(pmax, p0[15], p1[0]);
; #pragma unroll
;     for (int r = 1; r < 15; r += 2) pmax = max3f(pmax, p1[r], p1[r + 1]);
;     pmax = fmaxf(pmax, p1[15]);
;     { auto rr = __builtin_amdgcn_permlane32_swap(__float_as_uint(pmax), __float_as_uint(pmax), false, false);
;       pmax = fmaxf(__uint_as_float(rr[0]), __uint_as_float(rr[1])); }
;     if (!first && __builtin_expect(__all(pmax <= THR2), 1)) { alpha = 1.f; }
.LBB0_1236:
	s_min_u32 s10, s61, 0x7f
	s_lshl_b32 s10, s10, 6
	s_add_i32 s16, s10, 0x100
	s_add_i32 s38, s60, 0xffffa000
	s_mul_i32 s10, s16, 0x600
	s_add_u32 s10, s58, s10
	s_addc_u32 s11, s59, 0
	s_lshl_b32 s16, s16, 10
	v_lshl_add_u64 v[48:49], v[148:149], 0, s[16:17]
	global_load_dwordx4 v[112:115], v[48:49], off
	global_load_dwordx4 v[108:111], v146, s[10:11]
	global_load_dwordx4 v[104:107], v200, s[10:11]
	s_waitcnt lgkmcnt(0)
	s_barrier
	s_or_b32 s10, s61, 1
	s_and_b32 s11, s10, 0xff
	s_mulk_i32 s11, 0xab
	s_bfe_u32 s11, s11, 0x70009
	s_mul_i32 s11, s11, 3
	s_sub_i32 s10, s10, s11
	s_and_b32 s10, s10, 0xff
	s_mulk_i32 s10, 0x4400
	v_add_u32_e32 v52, s10, v152
	ds_read_b128 v[48:51], v52 offset:32768
	ds_read_b128 v[162:165], v52 offset:32800
	ds_read_b128 v[166:169], v52 offset:41472
	ds_read_b128 v[170:173], v52 offset:41504
	ds_read_b128 v[174:177], v52 offset:32832
	ds_read_b128 v[178:181], v52 offset:32864
	ds_read_b128 v[182:185], v52 offset:41536
	ds_read_b128 v[186:189], v52 offset:41568
	ds_read_b128 v[190:193], v52 offset:32896
	ds_read_b128 v[194:197], v52 offset:32928
	ds_read_b128 v[202:205], v52 offset:41600
	ds_read_b128 v[210:213], v52 offset:41632
	s_and_b32 s10, s38, 0x4000
	s_waitcnt lgkmcnt(11)
	v_mfma_f32_32x32x16_bf16 v[64:79], v[48:51], v[80:83], v[32:47]
	s_waitcnt lgkmcnt(9)
	v_mfma_f32_32x32x16_bf16 v[48:63], v[166:169], v[80:83], v[32:47]
	v_mfma_f32_32x32x16_bf16 v[64:79], v[162:165], v[84:87], v[64:79]
	s_waitcnt lgkmcnt(8)
	v_mfma_f32_32x32x16_bf16 v[48:63], v[170:173], v[84:87], v[48:63]
	s_waitcnt lgkmcnt(7)
	v_mfma_f32_32x32x16_bf16 v[64:79], v[174:177], v[88:91], v[64:79]
	s_waitcnt lgkmcnt(5)
	v_mfma_f32_32x32x16_bf16 v[48:63], v[182:185], v[88:91], v[48:63]
	v_add_u32_e32 v161, s10, v155
	s_waitcnt lgkmcnt(4)
	s_waitcnt lgkmcnt(3)
	s_waitcnt lgkmcnt(1)
	s_waitcnt lgkmcnt(0)
	ds_read_b64_tr_b16 v[162:163], v161 offset:0
	ds_read_b64_tr_b16 v[164:165], v161 offset:0x400
	ds_read_b64_tr_b16 v[166:167], v161 offset:0x800
	ds_read_b64_tr_b16 v[168:169], v161 offset:0xc00
	ds_read_b64_tr_b16 v[170:171], v161 offset:0x1000
	ds_read_b64_tr_b16 v[172:173], v161 offset:0x1400
	ds_read_b64_tr_b16 v[174:175], v161 offset:0x1800
	ds_read_b64_tr_b16 v[176:177], v161 offset:0x1c00
	ds_read_b64_tr_b16 v[182:183], v161 offset:0x200
	ds_read_b64_tr_b16 v[184:185], v161 offset:0x600
	ds_read_b64_tr_b16 v[214:215], v161 offset:0xa00
	ds_read_b64_tr_b16 v[216:217], v161 offset:0xe00
	ds_read_b64_tr_b16 v[218:219], v161 offset:0x1200
	ds_read_b64_tr_b16 v[220:221], v161 offset:0x1600
	ds_read_b64_tr_b16 v[222:223], v161 offset:0x1a00
	ds_read_b64_tr_b16 v[224:225], v161 offset:0x1e00
	s_nop 0
	v_mfma_f32_32x32x16_bf16 v[64:79], v[178:181], v[92:95], v[64:79]
	v_mfma_f32_32x32x16_bf16 v[48:63], v[186:189], v[92:95], v[48:63]
	v_mfma_f32_32x32x16_bf16 v[64:79], v[190:193], v[96:99], v[64:79]
	v_mfma_f32_32x32x16_bf16 v[48:63], v[202:205], v[96:99], v[48:63]
	v_mfma_f32_32x32x16_bf16 v[64:79], v[194:197], v[100:103], v[64:79]
	v_mfma_f32_32x32x16_bf16 v[48:63], v[210:213], v[100:103], v[48:63]
	s_waitcnt lgkmcnt(0)
	v_mfma_f32_32x32x16_bf16 v[0:15], v[140:143], v[162:165], v[0:15]
	v_mfma_f32_32x32x16_bf16 v[16:31], v[140:143], v[182:185], v[16:31]
	v_mfma_f32_32x32x16_bf16 v[0:15], v[136:139], v[166:169], v[0:15]
	v_mfma_f32_32x32x16_bf16 v[16:31], v[136:139], v[214:217], v[16:31]
	v_mfma_f32_32x32x16_bf16 v[0:15], v[132:135], v[170:173], v[0:15]
	v_mfma_f32_32x32x16_bf16 v[16:31], v[132:135], v[218:221], v[16:31]
	v_mfma_f32_32x32x16_bf16 v[0:15], v[128:131], v[174:177], v[0:15]
	v_mfma_f32_32x32x16_bf16 v[16:31], v[128:131], v[222:225], v[16:31]
	s_barrier
	s_nop 1
	v_max3_f32 v128, v64, v65, v66
	v_max3_f32 v129, v49, v50, v51
	v_max3_f32 v128, v128, v67, v68
	v_max3_f32 v129, v129, v52, v53
	v_max3_f32 v128, v128, v69, v70
	v_max3_f32 v129, v129, v54, v55
	v_max3_f32 v128, v128, v71, v72
	v_max3_f32 v129, v129, v56, v57
	v_max3_f32 v128, v128, v73, v74
	v_max3_f32 v129, v129, v58, v59
	v_max3_f32 v128, v128, v75, v76
	v_max3_f32 v129, v129, v60, v61
	v_max3_f32 v128, v128, v77, v78
	v_max3_f32 v129, v129, v62, v63
	v_max3_f32 v128, v128, v79, v48
	v_max_f32_e32 v128, v128, v129
	v_mov_b32_e32 v129, v128
	s_nop 1
	v_permlane32_swap_b32_e32 v128, v129
	v_max_f32_e32 v128, v128, v129
	v_cmp_ge_f32_e32 vcc, s83, v128
	v_mov_b32_e32 v161, 1.0
	s_cmp_eq_u64 vcc, exec
	s_cbranch_scc1 .LBB0_1241
	s_branch .LBB0_1245

; #define SBAR() __builtin_amdgcn_sched_barrier(0)
; #define PK4(P, BASE, OUT) do { u32x4 w = {cvtpk_a(P[BASE + 0], P[BASE + 1]), cvtpk_a(P[BASE + 2], P[BASE + 3]), cvtpk_a(P[BASE + 4], P[BASE + 5]), cvtpk_a(P[BASE + 6], P[BASE + 7])}; \
;     OUT = *reinterpret_cast<bf16x8*>(&w); } while (0)
; #define SWAIT() asm volatile("s_waitcnt vmcnt(3)" ::: "memory")
; __device__ __forceinline__ float exp_pack(f32x16& p0, f32x16& p1, bf16x8& pa0, bf16x8& pa1, bf16x8& pa2, bf16x8& pa3) {
; #pragma unroll
;     for (int r = 0; r < 16; ++r) p0[r] = __builtin_amdgcn_exp2f(p0[r]);
; #pragma unroll
;     for (int r = 0; r < 16; ++r) p1[r] = __builtin_amdgcn_exp2f(p1[r]);
;     SBAR(); asm volatile("s_nop 1" ::: "memory"); SBAR();
;     ...
;     PK4(p0, 0, pa0); PK4(p0, 8, pa1); PK4(p1, 0, pa2); PK4(p1, 8, pa3);
;     ...
;     float ps0 = p0[0], ps1 = p1[0];
; #pragma unroll
;     for (int r = 1; r < 16; ++r) { ps0 += p0[r]; ps1 += p1[r]; }
;     float ps = ps0 + ps1;
;     { auto rr = __builtin_amdgcn_permlane32_swap(__float_as_uint(ps), __float_as_uint(ps), false, false);
;       ps = __uint_as_float(rr[0]) + __uint_as_float(rr[1]); }
;     return ps;
; template <bool MLA>
; __device__ __forceinline__ void attn_core(const bf16_t* __restrict__ Qb, const bf16_t* __restrict__ Kh, const bf16_t* __restrict__ Vh, int seq, char* lds,
;                                           f32x16 (&o)[Cfg<MLA>::NCB], const int wid  , const int g  ) {
;     ...
;         SWAIT(); if (j + 3 < NT) SWRITE(((j + 3) % 3) * SHM_K, ((j + 3) & 3) * SHM_V, SO);
.LBB0_1241:
	v_exp_f32_e32 v48, v48
	v_exp_f32_e32 v49, v49
	v_exp_f32_e32 v64, v64
	v_exp_f32_e32 v65, v65
	v_exp_f32_e32 v66, v66
	v_exp_f32_e32 v67, v67
	v_exp_f32_e32 v68, v68
	v_exp_f32_e32 v69, v69
	v_exp_f32_e32 v70, v70
	v_exp_f32_e32 v71, v71
	v_exp_f32_e32 v72, v72
	v_exp_f32_e32 v73, v73
	v_exp_f32_e32 v74, v74
	v_exp_f32_e32 v75, v75
	v_exp_f32_e32 v76, v76
	v_exp_f32_e32 v77, v77
	v_exp_f32_e32 v78, v78
	v_exp_f32_e32 v79, v79
	v_exp_f32_e32 v50, v50
	v_exp_f32_e32 v51, v51
	v_exp_f32_e32 v52, v52
	v_exp_f32_e32 v53, v53
	v_exp_f32_e32 v54, v54
	v_exp_f32_e32 v55, v55
	v_exp_f32_e32 v56, v56
	v_exp_f32_e32 v57, v57
	v_exp_f32_e32 v58, v58
	v_exp_f32_e32 v59, v59
	v_exp_f32_e32 v60, v60
	v_exp_f32_e32 v61, v61
	v_exp_f32_e32 v62, v62
	v_exp_f32_e32 v63, v63
	s_nop 1
	v_cvt_pk_bf16_f32 v140, v64, v65
	v_cvt_pk_bf16_f32 v141, v66, v67
	v_cvt_pk_bf16_f32 v142, v68, v69
	v_cvt_pk_bf16_f32 v143, v70, v71
	v_cvt_pk_bf16_f32 v136, v72, v73
	v_cvt_pk_bf16_f32 v137, v74, v75
	v_cvt_pk_bf16_f32 v138, v76, v77
	v_cvt_pk_bf16_f32 v139, v78, v79
	v_cvt_pk_bf16_f32 v132, v48, v49
	v_add_f32_e32 v64, v64, v65
	v_add_f32_e32 v48, v48, v49
	v_add_f32_e32 v49, v66, v64
	v_add_f32_e32 v48, v50, v48
	v_add_f32_e32 v49, v67, v49
	v_add_f32_e32 v48, v51, v48
	v_add_f32_e32 v49, v68, v49
	v_add_f32_e32 v48, v52, v48
	v_add_f32_e32 v49, v69, v49
	v_add_f32_e32 v48, v53, v48
	v_add_f32_e32 v49, v70, v49
	v_add_f32_e32 v48, v54, v48
	v_add_f32_e32 v49, v71, v49
	v_add_f32_e32 v48, v55, v48
	v_add_f32_e32 v49, v72, v49
	v_add_f32_e32 v48, v56, v48
	v_add_f32_e32 v49, v73, v49
	v_add_f32_e32 v48, v57, v48
	v_add_f32_e32 v49, v74, v49
	v_add_f32_e32 v48, v58, v48
	v_add_f32_e32 v49, v75, v49
	v_add_f32_e32 v48, v59, v48
	v_add_f32_e32 v49, v76, v49
	v_add_f32_e32 v48, v60, v48
	v_add_f32_e32 v49, v77, v49
	v_add_f32_e32 v48, v61, v48
	v_add_f32_e32 v49, v78, v49
	v_add_f32_e32 v48, v62, v48
	v_add_f32_e32 v49, v79, v49
	v_add_f32_e32 v48, v63, v48
	v_cvt_pk_bf16_f32 v133, v50, v51
	v_cvt_pk_bf16_f32 v134, v52, v53
	v_cvt_pk_bf16_f32 v135, v54, v55
	v_cvt_pk_bf16_f32 v128, v56, v57
	v_cvt_pk_bf16_f32 v129, v58, v59
	v_cvt_pk_bf16_f32 v130, v60, v61
	v_cvt_pk_bf16_f32 v131, v62, v63
	v_add_f32_e32 v48, v48, v49
	s_waitcnt vmcnt(3)
	s_cmpk_gt_u32 s61, 0x80
	s_cbranch_scc1 .LBB0_1227
	s_mul_i32 s10, s51, 0xab
	s_bfe_u32 s10, s10, 0x70009
	s_mul_i32 s10, s10, 3
	s_sub_i32 s10, s51, s10
	s_and_b32 s10, s10, 0xff
	s_mulk_i32 s10, 0x4400
	v_add_u32_e32 v50, s62, v145
	s_add_i32 s16, s10, 0
	s_waitcnt vmcnt(5)
	ds_write_b128 v50, v[116:119]
	v_add_u32_e32 v50, s16, v144
	s_and_b64 vcc, exec, s[4:5]
	s_waitcnt vmcnt(4)
	ds_write_b128 v50, v[124:127] offset:32768
	s_cbranch_vccnz .LBB0_1227
	v_add_u32_e32 v50, s16, v150
	s_waitcnt vmcnt(3)
	ds_write_b128 v50, v[120:123] offset:32768
	s_branch .LBB0_1227

; template <bool MLA>
; __device__ __forceinline__ void attn_core(const bf16_t* __restrict__ Qb, const bf16_t* __restrict__ Kh, const bf16_t* __restrict__ Vh, int seq, char* lds,
;                                           f32x16 (&o)[Cfg<MLA>::NCB], const int wid  , const int g  ) {
;     ...
;     asm volatile("s_waitcnt vmcnt(0)" ::: "memory");
;     if (hi == 0) li_l[r32] = l_reg; asm volatile("s_waitcnt lgkmcnt(0)" ::: "memory");
.LBB0_1248:
	s_waitcnt vmcnt(0)
	v_mov_b32_e32 v50, v157
	s_nop 1
	v_permlane32_swap_b32_e32 v157, v50
	v_add_f32_e32 v157, v157, v50
	s_and_saveexec_b64 s[4:5], s[6:7]
	s_cbranch_execz .LBB0_1139
	ds_write_b32 v156, v157
	s_branch .LBB0_1139
